# RMS-norm + modulate phases rewritten: rows of four items and the gain/scale/shift vectors requested up front instead of one latency-exposed item at a time
# speedup vs baseline: 1.1284x; 1.0067x over previous
.LBB0_46:
	s_andn2_b64 vcc, exec, s[4:5]
	s_cbranch_vccnz .LBB0_50
	v_readlane_b32 s4, v239, 7
	v_readlane_b32 s5, v239, 8
	s_andn2_b64 vcc, exec, s[4:5]
	s_cbranch_vccnz .LBB0_50
	s_mov_b32 s25, s66
.Lnb1_again:
	v_and_b32_e32 v0, 63, v133
	v_lshrrev_b32_e32 v234, 6, v133
	v_lshlrev_b32_e32 v195, 4, v0
	v_readfirstlane_b32 s29, v234
	v_add_u32_e32 v240, 0x1000, v195
	v_lshlrev_b32_e32 v241, 3, v0
	s_lshl_b32 s29, s29, 1
	s_load_dwordx2 s[20:21], s[0:1], 0x68
	s_lshl_b32 s26, s62, 12
	s_waitcnt lgkmcnt(0)
	s_add_u32 s20, s20, s26
	s_addc_u32 s21, s21, 0
	global_load_dwordx4 v[134:137], v195, s[20:21]
	global_load_dwordx4 v[138:141], v195, s[20:21] offset:1024
	global_load_dwordx4 v[142:145], v195, s[20:21] offset:2048
	global_load_dwordx4 v[146:149], v195, s[20:21] offset:3072
	s_mov_b32 s26, s25
	s_mov_b32 s7, 0
	s_cmp_ge_u32 s26, 2048
	s_cbranch_scc1 .Lnb1_xdone
	s_lshl_b32 s27, s26, 3
	s_add_u32 s27, s27, s29
	s_load_dwordx2 s[20:21], s[0:1], 0x128
	s_lshl_b32 s27, s27, 12
	s_waitcnt lgkmcnt(0)
	s_add_u32 s20, s20, s27
	s_addc_u32 s21, s21, 0
	global_load_dwordx4 v[2:5], v195, s[20:21]
	global_load_dwordx4 v[6:9], v195, s[20:21] offset:1024
	global_load_dwordx4 v[10:13], v195, s[20:21] offset:2048
	global_load_dwordx4 v[14:17], v195, s[20:21] offset:3072
	global_load_dwordx4 v[18:21], v240, s[20:21]
	global_load_dwordx4 v[22:25], v240, s[20:21] offset:1024
	global_load_dwordx4 v[26:29], v240, s[20:21] offset:2048
	global_load_dwordx4 v[30:33], v240, s[20:21] offset:3072
	s_add_u32 s7, s7, 1
	s_add_u32 s26, s26, s42
	s_cmp_ge_u32 s26, 2048
	s_cbranch_scc1 .Lnb1_xdone
	s_lshl_b32 s27, s26, 3
	s_add_u32 s27, s27, s29
	s_load_dwordx2 s[20:21], s[0:1], 0x128
	s_lshl_b32 s27, s27, 12
	s_waitcnt lgkmcnt(0)
	s_add_u32 s20, s20, s27
	s_addc_u32 s21, s21, 0
	global_load_dwordx4 v[34:37], v195, s[20:21]
	global_load_dwordx4 v[38:41], v195, s[20:21] offset:1024
	global_load_dwordx4 v[42:45], v195, s[20:21] offset:2048
	global_load_dwordx4 v[46:49], v195, s[20:21] offset:3072
	global_load_dwordx4 v[50:53], v240, s[20:21]
	global_load_dwordx4 v[54:57], v240, s[20:21] offset:1024
	global_load_dwordx4 v[58:61], v240, s[20:21] offset:2048
	global_load_dwordx4 v[62:65], v240, s[20:21] offset:3072
	s_add_u32 s7, s7, 1
	s_add_u32 s26, s26, s42
	s_cmp_ge_u32 s26, 2048
	s_cbranch_scc1 .Lnb1_xdone
	s_lshl_b32 s27, s26, 3
	s_add_u32 s27, s27, s29
	s_load_dwordx2 s[20:21], s[0:1], 0x128
	s_lshl_b32 s27, s27, 12
	s_waitcnt lgkmcnt(0)
	s_add_u32 s20, s20, s27
	s_addc_u32 s21, s21, 0
	global_load_dwordx4 v[66:69], v195, s[20:21]
	global_load_dwordx4 v[70:73], v195, s[20:21] offset:1024
	global_load_dwordx4 v[74:77], v195, s[20:21] offset:2048
	global_load_dwordx4 v[78:81], v195, s[20:21] offset:3072
	global_load_dwordx4 v[82:85], v240, s[20:21]
	global_load_dwordx4 v[86:89], v240, s[20:21] offset:1024
	global_load_dwordx4 v[90:93], v240, s[20:21] offset:2048
	global_load_dwordx4 v[94:97], v240, s[20:21] offset:3072
	s_add_u32 s7, s7, 1
	s_add_u32 s26, s26, s42
	s_cmp_ge_u32 s26, 2048
	s_cbranch_scc1 .Lnb1_xdone
	s_lshl_b32 s27, s26, 3
	s_add_u32 s27, s27, s29
	s_load_dwordx2 s[20:21], s[0:1], 0x128
	s_lshl_b32 s27, s27, 12
	s_waitcnt lgkmcnt(0)
	s_add_u32 s20, s20, s27
	s_addc_u32 s21, s21, 0
	global_load_dwordx4 v[98:101], v195, s[20:21]
	global_load_dwordx4 v[102:105], v195, s[20:21] offset:1024
	global_load_dwordx4 v[106:109], v195, s[20:21] offset:2048
	global_load_dwordx4 v[110:113], v195, s[20:21] offset:3072
	global_load_dwordx4 v[114:117], v240, s[20:21]
	global_load_dwordx4 v[118:121], v240, s[20:21] offset:1024
	global_load_dwordx4 v[122:125], v240, s[20:21] offset:2048
	global_load_dwordx4 v[126:129], v240, s[20:21] offset:3072
	s_add_u32 s7, s7, 1
	s_add_u32 s26, s26, s42
.Lnb1_xdone:
	s_mov_b32 s26, s25
	s_load_dwordx2 s[20:21], s[0:1], 0x130
	s_lshr_b32 s27, s26, 9
	s_max_u32 s27, s27, 1
	s_sub_u32 s27, s27, 1
	s_mul_i32 s28, s62, 3
	s_add_u32 s27, s27, s28
	s_mul_i32 s27, s27, 24576
	s_waitcnt lgkmcnt(0)
	s_add_u32 s20, s20, s27
	s_addc_u32 s21, s21, 0
	s_add_u32 s18, s20, 0x4000
	s_addc_u32 s19, s21, 0
	global_load_dwordx4 v[150:153], v195, s[18:19]
	global_load_dwordx4 v[154:157], v195, s[18:19] offset:1024
	global_load_dwordx4 v[158:161], v195, s[18:19] offset:2048
	global_load_dwordx4 v[162:165], v195, s[18:19] offset:3072
	s_add_u32 s18, s20, 0x3000
	s_addc_u32 s19, s21, 0
	global_load_dwordx4 v[166:169], v195, s[18:19]
	global_load_dwordx4 v[170:173], v195, s[18:19] offset:1024
	global_load_dwordx4 v[174:177], v195, s[18:19] offset:2048
	global_load_dwordx4 v[178:181], v195, s[18:19] offset:3072
	s_mul_i32 s6, s42, 0
	s_add_u32 s6, s6, s25
	s_add_u32 s26, s6, s42
	s_min_u32 s26, s26, 2047
	s_load_dwordx2 s[20:21], s[0:1], 0x130
	s_lshr_b32 s27, s26, 9
	s_max_u32 s27, s27, 1
	s_sub_u32 s27, s27, 1
	s_mul_i32 s28, s62, 3
	s_add_u32 s27, s27, s28
	s_mul_i32 s27, s27, 24576
	s_waitcnt lgkmcnt(0)
	s_add_u32 s20, s20, s27
	s_addc_u32 s21, s21, 0
	s_add_u32 s18, s20, 0x4000
	s_addc_u32 s19, s21, 0
	global_load_dwordx4 v[196:199], v195, s[18:19]
	global_load_dwordx4 v[200:203], v195, s[18:19] offset:1024
	global_load_dwordx4 v[204:207], v195, s[18:19] offset:2048
	global_load_dwordx4 v[212:215], v195, s[18:19] offset:3072
	s_add_u32 s18, s20, 0x3000
	s_addc_u32 s19, s21, 0
	global_load_dwordx4 v[216:219], v195, s[18:19]
	global_load_dwordx4 v[220:223], v195, s[18:19] offset:1024
	global_load_dwordx4 v[224:227], v195, s[18:19] offset:2048
	global_load_dwordx4 v[228:231], v195, s[18:19] offset:3072
	s_waitcnt vmcnt(8)
	v_pk_mul_f32 v[234:235], v[2:3], v[2:3]
	v_pk_mul_f32 v[236:237], v[4:5], v[4:5]
	v_pk_fma_f32 v[234:235], v[6:7], v[6:7], v[234:235]
	v_pk_fma_f32 v[236:237], v[8:9], v[8:9], v[236:237]
	v_pk_fma_f32 v[234:235], v[10:11], v[10:11], v[234:235]
	v_pk_fma_f32 v[236:237], v[12:13], v[12:13], v[236:237]
	v_pk_fma_f32 v[234:235], v[14:15], v[14:15], v[234:235]
	v_pk_fma_f32 v[236:237], v[16:17], v[16:17], v[236:237]
	v_pk_add_f32 v[234:235], v[234:235], v[236:237]
	v_add_f32_e32 v232, v234, v235
	v_pk_mul_f32 v[234:235], v[18:19], v[18:19]
	v_pk_mul_f32 v[236:237], v[20:21], v[20:21]
	v_pk_fma_f32 v[234:235], v[22:23], v[22:23], v[234:235]
	v_pk_fma_f32 v[236:237], v[24:25], v[24:25], v[236:237]
	v_pk_fma_f32 v[234:235], v[26:27], v[26:27], v[234:235]
	v_pk_fma_f32 v[236:237], v[28:29], v[28:29], v[236:237]
	v_pk_fma_f32 v[234:235], v[30:31], v[30:31], v[234:235]
	v_pk_fma_f32 v[236:237], v[32:33], v[32:33], v[236:237]
	v_pk_add_f32 v[234:235], v[234:235], v[236:237]
	v_add_f32_e32 v233, v234, v235
	s_nop 1
	v_add_f32_dpp v232, v232, v232 quad_perm:[1,0,3,2] row_mask:0xf bank_mask:0xf bound_ctrl:1
	s_nop 1
	v_add_f32_dpp v232, v232, v232 quad_perm:[2,3,0,1] row_mask:0xf bank_mask:0xf bound_ctrl:1
	s_nop 1
	v_add_f32_dpp v232, v232, v232 row_half_mirror row_mask:0xf bank_mask:0xf bound_ctrl:1
	s_nop 1
	v_add_f32_dpp v232, v232, v232 row_mirror row_mask:0xf bank_mask:0xf bound_ctrl:1
	s_nop 1
	v_readlane_b32 s18, v232, 0
	v_readlane_b32 s19, v232, 16
	v_readlane_b32 s27, v232, 32
	v_readlane_b32 s28, v232, 48
	s_nop 3
	v_mov_b32_e32 v234, s19
	v_mov_b32_e32 v235, s28
	v_add_f32_e32 v234, s18, v234
	v_add_f32_e32 v235, s27, v235
	v_add_f32_e32 v234, v234, v235
	v_mov_b32_e32 v235, 0x3a800000
	v_fma_f32 v234, v234, v235, v132
	v_rsq_f32_e32 v232, v234
	s_nop 1
	v_add_f32_dpp v233, v233, v233 quad_perm:[1,0,3,2] row_mask:0xf bank_mask:0xf bound_ctrl:1
	s_nop 1
	v_add_f32_dpp v233, v233, v233 quad_perm:[2,3,0,1] row_mask:0xf bank_mask:0xf bound_ctrl:1
	s_nop 1
	v_add_f32_dpp v233, v233, v233 row_half_mirror row_mask:0xf bank_mask:0xf bound_ctrl:1
	s_nop 1
	v_add_f32_dpp v233, v233, v233 row_mirror row_mask:0xf bank_mask:0xf bound_ctrl:1
	s_nop 1
	v_readlane_b32 s18, v233, 0
	v_readlane_b32 s19, v233, 16
	v_readlane_b32 s27, v233, 32
	v_readlane_b32 s28, v233, 48
	s_nop 3
	v_mov_b32_e32 v234, s19
	v_mov_b32_e32 v235, s28
	v_add_f32_e32 v234, s18, v234
	v_add_f32_e32 v235, s27, v235
	v_add_f32_e32 v234, v234, v235
	v_mov_b32_e32 v235, 0x3a800000
	v_fma_f32 v234, v234, v235, v132
	v_rsq_f32_e32 v233, v234
	s_load_dwordx2 s[18:19], s[0:1], 0x130
	s_lshl_b32 s27, s6, 3
	s_add_u32 s27, s27, s29
	s_lshl_b32 s27, s27, 11
	s_add_u32 s27, s27, 0x2b27800
	s_waitcnt lgkmcnt(0)
	s_add_u32 s18, s18, s27
	s_addc_u32 s19, s19, 0
	v_mul_f32_e32 v2, v232, v2
	v_mul_f32_e32 v3, v232, v3
	v_mul_f32_e32 v4, v232, v4
	v_mul_f32_e32 v5, v232, v5
	v_pk_mul_f32 v[2:3], v[2:3], v[134:135]
	v_pk_mul_f32 v[4:5], v[4:5], v[136:137]
	v_pk_add_f32 v[234:235], v[150:151], 1.0 op_sel_hi:[1,0]
	v_pk_add_f32 v[236:237], v[152:153], 1.0 op_sel_hi:[1,0]
	v_pk_fma_f32 v[2:3], v[2:3], v[234:235], v[166:167]
	v_pk_fma_f32 v[4:5], v[4:5], v[236:237], v[168:169]
	v_cvt_pk_bf16_f32 v2, v2, v3
	v_cvt_pk_bf16_f32 v3, v4, v5
	global_store_dwordx2 v241, v[2:3], s[18:19] offset:0
	v_mul_f32_e32 v6, v232, v6
	v_mul_f32_e32 v7, v232, v7
	v_mul_f32_e32 v8, v232, v8
	v_mul_f32_e32 v9, v232, v9
	v_pk_mul_f32 v[6:7], v[6:7], v[138:139]
	v_pk_mul_f32 v[8:9], v[8:9], v[140:141]
	v_pk_add_f32 v[234:235], v[154:155], 1.0 op_sel_hi:[1,0]
	v_pk_add_f32 v[236:237], v[156:157], 1.0 op_sel_hi:[1,0]
	v_pk_fma_f32 v[6:7], v[6:7], v[234:235], v[170:171]
	v_pk_fma_f32 v[8:9], v[8:9], v[236:237], v[172:173]
	v_cvt_pk_bf16_f32 v6, v6, v7
	v_cvt_pk_bf16_f32 v7, v8, v9
	global_store_dwordx2 v241, v[6:7], s[18:19] offset:512
	v_mul_f32_e32 v10, v232, v10
	v_mul_f32_e32 v11, v232, v11
	v_mul_f32_e32 v12, v232, v12
	v_mul_f32_e32 v13, v232, v13
	v_pk_mul_f32 v[10:11], v[10:11], v[142:143]
	v_pk_mul_f32 v[12:13], v[12:13], v[144:145]
	v_pk_add_f32 v[234:235], v[158:159], 1.0 op_sel_hi:[1,0]
	v_pk_add_f32 v[236:237], v[160:161], 1.0 op_sel_hi:[1,0]
	v_pk_fma_f32 v[10:11], v[10:11], v[234:235], v[174:175]
	v_pk_fma_f32 v[12:13], v[12:13], v[236:237], v[176:177]
	v_cvt_pk_bf16_f32 v10, v10, v11
	v_cvt_pk_bf16_f32 v11, v12, v13
	global_store_dwordx2 v241, v[10:11], s[18:19] offset:1024
	v_mul_f32_e32 v14, v232, v14
	v_mul_f32_e32 v15, v232, v15
	v_mul_f32_e32 v16, v232, v16
	v_mul_f32_e32 v17, v232, v17
	v_pk_mul_f32 v[14:15], v[14:15], v[146:147]
	v_pk_mul_f32 v[16:17], v[16:17], v[148:149]
	v_pk_add_f32 v[234:235], v[162:163], 1.0 op_sel_hi:[1,0]
	v_pk_add_f32 v[236:237], v[164:165], 1.0 op_sel_hi:[1,0]
	v_pk_fma_f32 v[14:15], v[14:15], v[234:235], v[178:179]
	v_pk_fma_f32 v[16:17], v[16:17], v[236:237], v[180:181]
	v_cvt_pk_bf16_f32 v14, v14, v15
	v_cvt_pk_bf16_f32 v15, v16, v17
	global_store_dwordx2 v241, v[14:15], s[18:19] offset:1536
	v_mul_f32_e32 v18, v233, v18
	v_mul_f32_e32 v19, v233, v19
	v_mul_f32_e32 v20, v233, v20
	v_mul_f32_e32 v21, v233, v21
	v_pk_mul_f32 v[18:19], v[18:19], v[134:135]
	v_pk_mul_f32 v[20:21], v[20:21], v[136:137]
	v_pk_add_f32 v[234:235], v[150:151], 1.0 op_sel_hi:[1,0]
	v_pk_add_f32 v[236:237], v[152:153], 1.0 op_sel_hi:[1,0]
	v_pk_fma_f32 v[18:19], v[18:19], v[234:235], v[166:167]
	v_pk_fma_f32 v[20:21], v[20:21], v[236:237], v[168:169]
	v_cvt_pk_bf16_f32 v18, v18, v19
	v_cvt_pk_bf16_f32 v19, v20, v21
	global_store_dwordx2 v241, v[18:19], s[18:19] offset:2048
	v_mul_f32_e32 v22, v233, v22
	v_mul_f32_e32 v23, v233, v23
	v_mul_f32_e32 v24, v233, v24
	v_mul_f32_e32 v25, v233, v25
	v_pk_mul_f32 v[22:23], v[22:23], v[138:139]
	v_pk_mul_f32 v[24:25], v[24:25], v[140:141]
	v_pk_add_f32 v[234:235], v[154:155], 1.0 op_sel_hi:[1,0]
	v_pk_add_f32 v[236:237], v[156:157], 1.0 op_sel_hi:[1,0]
	v_pk_fma_f32 v[22:23], v[22:23], v[234:235], v[170:171]
	v_pk_fma_f32 v[24:25], v[24:25], v[236:237], v[172:173]
	v_cvt_pk_bf16_f32 v22, v22, v23
	v_cvt_pk_bf16_f32 v23, v24, v25
	global_store_dwordx2 v241, v[22:23], s[18:19] offset:2560
	v_mul_f32_e32 v26, v233, v26
	v_mul_f32_e32 v27, v233, v27
	v_mul_f32_e32 v28, v233, v28
	v_mul_f32_e32 v29, v233, v29
	v_pk_mul_f32 v[26:27], v[26:27], v[142:143]
	v_pk_mul_f32 v[28:29], v[28:29], v[144:145]
	v_pk_add_f32 v[234:235], v[158:159], 1.0 op_sel_hi:[1,0]
	v_pk_add_f32 v[236:237], v[160:161], 1.0 op_sel_hi:[1,0]
	v_pk_fma_f32 v[26:27], v[26:27], v[234:235], v[174:175]
	v_pk_fma_f32 v[28:29], v[28:29], v[236:237], v[176:177]
	v_cvt_pk_bf16_f32 v26, v26, v27
	v_cvt_pk_bf16_f32 v27, v28, v29
	global_store_dwordx2 v241, v[26:27], s[18:19] offset:3072
	v_mul_f32_e32 v30, v233, v30
	v_mul_f32_e32 v31, v233, v31
	v_mul_f32_e32 v32, v233, v32
	v_mul_f32_e32 v33, v233, v33
	v_pk_mul_f32 v[30:31], v[30:31], v[146:147]
	v_pk_mul_f32 v[32:33], v[32:33], v[148:149]
	v_pk_add_f32 v[234:235], v[162:163], 1.0 op_sel_hi:[1,0]
	v_pk_add_f32 v[236:237], v[164:165], 1.0 op_sel_hi:[1,0]
	v_pk_fma_f32 v[30:31], v[30:31], v[234:235], v[178:179]
	v_pk_fma_f32 v[32:33], v[32:33], v[236:237], v[180:181]
	v_cvt_pk_bf16_f32 v30, v30, v31
	v_cvt_pk_bf16_f32 v31, v32, v33
	global_store_dwordx2 v241, v[30:31], s[18:19] offset:3584
	s_cmp_le_u32 s7, 1
	s_cbranch_scc1 .Lnb1_alldone
	s_mul_i32 s6, s42, 1
	s_add_u32 s6, s6, s25
	s_add_u32 s26, s6, s42
	s_min_u32 s26, s26, 2047
	s_load_dwordx2 s[20:21], s[0:1], 0x130
	s_lshr_b32 s27, s26, 9
	s_max_u32 s27, s27, 1
	s_sub_u32 s27, s27, 1
	s_mul_i32 s28, s62, 3
	s_add_u32 s27, s27, s28
	s_mul_i32 s27, s27, 24576
	s_waitcnt lgkmcnt(0)
	s_add_u32 s20, s20, s27
	s_addc_u32 s21, s21, 0
	s_add_u32 s18, s20, 0x4000
	s_addc_u32 s19, s21, 0
	global_load_dwordx4 v[150:153], v195, s[18:19]
	global_load_dwordx4 v[154:157], v195, s[18:19] offset:1024
	global_load_dwordx4 v[158:161], v195, s[18:19] offset:2048
	global_load_dwordx4 v[162:165], v195, s[18:19] offset:3072
	s_add_u32 s18, s20, 0x3000
	s_addc_u32 s19, s21, 0
	global_load_dwordx4 v[166:169], v195, s[18:19]
	global_load_dwordx4 v[170:173], v195, s[18:19] offset:1024
	global_load_dwordx4 v[174:177], v195, s[18:19] offset:2048
	global_load_dwordx4 v[178:181], v195, s[18:19] offset:3072
	s_waitcnt vmcnt(16)
	v_pk_mul_f32 v[234:235], v[34:35], v[34:35]
	v_pk_mul_f32 v[236:237], v[36:37], v[36:37]
	v_pk_fma_f32 v[234:235], v[38:39], v[38:39], v[234:235]
	v_pk_fma_f32 v[236:237], v[40:41], v[40:41], v[236:237]
	v_pk_fma_f32 v[234:235], v[42:43], v[42:43], v[234:235]
	v_pk_fma_f32 v[236:237], v[44:45], v[44:45], v[236:237]
	v_pk_fma_f32 v[234:235], v[46:47], v[46:47], v[234:235]
	v_pk_fma_f32 v[236:237], v[48:49], v[48:49], v[236:237]
	v_pk_add_f32 v[234:235], v[234:235], v[236:237]
	v_add_f32_e32 v232, v234, v235
	v_pk_mul_f32 v[234:235], v[50:51], v[50:51]
	v_pk_mul_f32 v[236:237], v[52:53], v[52:53]
	v_pk_fma_f32 v[234:235], v[54:55], v[54:55], v[234:235]
	v_pk_fma_f32 v[236:237], v[56:57], v[56:57], v[236:237]
	v_pk_fma_f32 v[234:235], v[58:59], v[58:59], v[234:235]
	v_pk_fma_f32 v[236:237], v[60:61], v[60:61], v[236:237]
	v_pk_fma_f32 v[234:235], v[62:63], v[62:63], v[234:235]
	v_pk_fma_f32 v[236:237], v[64:65], v[64:65], v[236:237]
	v_pk_add_f32 v[234:235], v[234:235], v[236:237]
	v_add_f32_e32 v233, v234, v235
	s_nop 1
	v_add_f32_dpp v232, v232, v232 quad_perm:[1,0,3,2] row_mask:0xf bank_mask:0xf bound_ctrl:1
	s_nop 1
	v_add_f32_dpp v232, v232, v232 quad_perm:[2,3,0,1] row_mask:0xf bank_mask:0xf bound_ctrl:1
	s_nop 1
	v_add_f32_dpp v232, v232, v232 row_half_mirror row_mask:0xf bank_mask:0xf bound_ctrl:1
	s_nop 1
	v_add_f32_dpp v232, v232, v232 row_mirror row_mask:0xf bank_mask:0xf bound_ctrl:1
	s_nop 1
	v_readlane_b32 s18, v232, 0
	v_readlane_b32 s19, v232, 16
	v_readlane_b32 s27, v232, 32
	v_readlane_b32 s28, v232, 48
	s_nop 3
	v_mov_b32_e32 v234, s19
	v_mov_b32_e32 v235, s28
	v_add_f32_e32 v234, s18, v234
	v_add_f32_e32 v235, s27, v235
	v_add_f32_e32 v234, v234, v235
	v_mov_b32_e32 v235, 0x3a800000
	v_fma_f32 v234, v234, v235, v132
	v_rsq_f32_e32 v232, v234
	s_nop 1
	v_add_f32_dpp v233, v233, v233 quad_perm:[1,0,3,2] row_mask:0xf bank_mask:0xf bound_ctrl:1
	s_nop 1
	v_add_f32_dpp v233, v233, v233 quad_perm:[2,3,0,1] row_mask:0xf bank_mask:0xf bound_ctrl:1
	s_nop 1
	v_add_f32_dpp v233, v233, v233 row_half_mirror row_mask:0xf bank_mask:0xf bound_ctrl:1
	s_nop 1
	v_add_f32_dpp v233, v233, v233 row_mirror row_mask:0xf bank_mask:0xf bound_ctrl:1
	s_nop 1
	v_readlane_b32 s18, v233, 0
	v_readlane_b32 s19, v233, 16
	v_readlane_b32 s27, v233, 32
	v_readlane_b32 s28, v233, 48
	s_nop 3
	v_mov_b32_e32 v234, s19
	v_mov_b32_e32 v235, s28
	v_add_f32_e32 v234, s18, v234
	v_add_f32_e32 v235, s27, v235
	v_add_f32_e32 v234, v234, v235
	v_mov_b32_e32 v235, 0x3a800000
	v_fma_f32 v234, v234, v235, v132
	v_rsq_f32_e32 v233, v234
	s_load_dwordx2 s[18:19], s[0:1], 0x130
	s_lshl_b32 s27, s6, 3
	s_add_u32 s27, s27, s29
	s_lshl_b32 s27, s27, 11
	s_add_u32 s27, s27, 0x2b27800
	s_waitcnt lgkmcnt(0)
	s_add_u32 s18, s18, s27
	s_addc_u32 s19, s19, 0
	v_mul_f32_e32 v34, v232, v34
	v_mul_f32_e32 v35, v232, v35
	v_mul_f32_e32 v36, v232, v36
	v_mul_f32_e32 v37, v232, v37
	v_pk_mul_f32 v[34:35], v[34:35], v[134:135]
	v_pk_mul_f32 v[36:37], v[36:37], v[136:137]
	v_pk_add_f32 v[234:235], v[196:197], 1.0 op_sel_hi:[1,0]
	v_pk_add_f32 v[236:237], v[198:199], 1.0 op_sel_hi:[1,0]
	v_pk_fma_f32 v[34:35], v[34:35], v[234:235], v[216:217]
	v_pk_fma_f32 v[36:37], v[36:37], v[236:237], v[218:219]
	v_cvt_pk_bf16_f32 v34, v34, v35
	v_cvt_pk_bf16_f32 v35, v36, v37
	global_store_dwordx2 v241, v[34:35], s[18:19] offset:0
	v_mul_f32_e32 v38, v232, v38
	v_mul_f32_e32 v39, v232, v39
	v_mul_f32_e32 v40, v232, v40
	v_mul_f32_e32 v41, v232, v41
	v_pk_mul_f32 v[38:39], v[38:39], v[138:139]
	v_pk_mul_f32 v[40:41], v[40:41], v[140:141]
	v_pk_add_f32 v[234:235], v[200:201], 1.0 op_sel_hi:[1,0]
	v_pk_add_f32 v[236:237], v[202:203], 1.0 op_sel_hi:[1,0]
	v_pk_fma_f32 v[38:39], v[38:39], v[234:235], v[220:221]
	v_pk_fma_f32 v[40:41], v[40:41], v[236:237], v[222:223]
	v_cvt_pk_bf16_f32 v38, v38, v39
	v_cvt_pk_bf16_f32 v39, v40, v41
	global_store_dwordx2 v241, v[38:39], s[18:19] offset:512
	v_mul_f32_e32 v42, v232, v42
	v_mul_f32_e32 v43, v232, v43
	v_mul_f32_e32 v44, v232, v44
	v_mul_f32_e32 v45, v232, v45
	v_pk_mul_f32 v[42:43], v[42:43], v[142:143]
	v_pk_mul_f32 v[44:45], v[44:45], v[144:145]
	v_pk_add_f32 v[234:235], v[204:205], 1.0 op_sel_hi:[1,0]
	v_pk_add_f32 v[236:237], v[206:207], 1.0 op_sel_hi:[1,0]
	v_pk_fma_f32 v[42:43], v[42:43], v[234:235], v[224:225]
	v_pk_fma_f32 v[44:45], v[44:45], v[236:237], v[226:227]
	v_cvt_pk_bf16_f32 v42, v42, v43
	v_cvt_pk_bf16_f32 v43, v44, v45
	global_store_dwordx2 v241, v[42:43], s[18:19] offset:1024
	v_mul_f32_e32 v46, v232, v46
	v_mul_f32_e32 v47, v232, v47
	v_mul_f32_e32 v48, v232, v48
	v_mul_f32_e32 v49, v232, v49
	v_pk_mul_f32 v[46:47], v[46:47], v[146:147]
	v_pk_mul_f32 v[48:49], v[48:49], v[148:149]
	v_pk_add_f32 v[234:235], v[212:213], 1.0 op_sel_hi:[1,0]
	v_pk_add_f32 v[236:237], v[214:215], 1.0 op_sel_hi:[1,0]
	v_pk_fma_f32 v[46:47], v[46:47], v[234:235], v[228:229]
	v_pk_fma_f32 v[48:49], v[48:49], v[236:237], v[230:231]
	v_cvt_pk_bf16_f32 v46, v46, v47
	v_cvt_pk_bf16_f32 v47, v48, v49
	global_store_dwordx2 v241, v[46:47], s[18:19] offset:1536
	v_mul_f32_e32 v50, v233, v50
	v_mul_f32_e32 v51, v233, v51
	v_mul_f32_e32 v52, v233, v52
	v_mul_f32_e32 v53, v233, v53
	v_pk_mul_f32 v[50:51], v[50:51], v[134:135]
	v_pk_mul_f32 v[52:53], v[52:53], v[136:137]
	v_pk_add_f32 v[234:235], v[196:197], 1.0 op_sel_hi:[1,0]
	v_pk_add_f32 v[236:237], v[198:199], 1.0 op_sel_hi:[1,0]
	v_pk_fma_f32 v[50:51], v[50:51], v[234:235], v[216:217]
	v_pk_fma_f32 v[52:53], v[52:53], v[236:237], v[218:219]
	v_cvt_pk_bf16_f32 v50, v50, v51
	v_cvt_pk_bf16_f32 v51, v52, v53
	global_store_dwordx2 v241, v[50:51], s[18:19] offset:2048
	v_mul_f32_e32 v54, v233, v54
	v_mul_f32_e32 v55, v233, v55
	v_mul_f32_e32 v56, v233, v56
	v_mul_f32_e32 v57, v233, v57
	v_pk_mul_f32 v[54:55], v[54:55], v[138:139]
	v_pk_mul_f32 v[56:57], v[56:57], v[140:141]
	v_pk_add_f32 v[234:235], v[200:201], 1.0 op_sel_hi:[1,0]
	v_pk_add_f32 v[236:237], v[202:203], 1.0 op_sel_hi:[1,0]
	v_pk_fma_f32 v[54:55], v[54:55], v[234:235], v[220:221]
	v_pk_fma_f32 v[56:57], v[56:57], v[236:237], v[222:223]
	v_cvt_pk_bf16_f32 v54, v54, v55
	v_cvt_pk_bf16_f32 v55, v56, v57
	global_store_dwordx2 v241, v[54:55], s[18:19] offset:2560
	v_mul_f32_e32 v58, v233, v58
	v_mul_f32_e32 v59, v233, v59
	v_mul_f32_e32 v60, v233, v60
	v_mul_f32_e32 v61, v233, v61
	v_pk_mul_f32 v[58:59], v[58:59], v[142:143]
	v_pk_mul_f32 v[60:61], v[60:61], v[144:145]
	v_pk_add_f32 v[234:235], v[204:205], 1.0 op_sel_hi:[1,0]
	v_pk_add_f32 v[236:237], v[206:207], 1.0 op_sel_hi:[1,0]
	v_pk_fma_f32 v[58:59], v[58:59], v[234:235], v[224:225]
	v_pk_fma_f32 v[60:61], v[60:61], v[236:237], v[226:227]
	v_cvt_pk_bf16_f32 v58, v58, v59
	v_cvt_pk_bf16_f32 v59, v60, v61
	global_store_dwordx2 v241, v[58:59], s[18:19] offset:3072
	v_mul_f32_e32 v62, v233, v62
	v_mul_f32_e32 v63, v233, v63
	v_mul_f32_e32 v64, v233, v64
	v_mul_f32_e32 v65, v233, v65
	v_pk_mul_f32 v[62:63], v[62:63], v[146:147]
	v_pk_mul_f32 v[64:65], v[64:65], v[148:149]
	v_pk_add_f32 v[234:235], v[212:213], 1.0 op_sel_hi:[1,0]
	v_pk_add_f32 v[236:237], v[214:215], 1.0 op_sel_hi:[1,0]
	v_pk_fma_f32 v[62:63], v[62:63], v[234:235], v[228:229]
	v_pk_fma_f32 v[64:65], v[64:65], v[236:237], v[230:231]
	v_cvt_pk_bf16_f32 v62, v62, v63
	v_cvt_pk_bf16_f32 v63, v64, v65
	global_store_dwordx2 v241, v[62:63], s[18:19] offset:3584
	s_cmp_le_u32 s7, 2
	s_cbranch_scc1 .Lnb1_alldone
	s_mul_i32 s6, s42, 2
	s_add_u32 s6, s6, s25
	s_add_u32 s26, s6, s42
	s_min_u32 s26, s26, 2047
	s_load_dwordx2 s[20:21], s[0:1], 0x130
	s_lshr_b32 s27, s26, 9
	s_max_u32 s27, s27, 1
	s_sub_u32 s27, s27, 1
	s_mul_i32 s28, s62, 3
	s_add_u32 s27, s27, s28
	s_mul_i32 s27, s27, 24576
	s_waitcnt lgkmcnt(0)
	s_add_u32 s20, s20, s27
	s_addc_u32 s21, s21, 0
	s_add_u32 s18, s20, 0x4000
	s_addc_u32 s19, s21, 0
	global_load_dwordx4 v[196:199], v195, s[18:19]
	global_load_dwordx4 v[200:203], v195, s[18:19] offset:1024
	global_load_dwordx4 v[204:207], v195, s[18:19] offset:2048
	global_load_dwordx4 v[212:215], v195, s[18:19] offset:3072
	s_add_u32 s18, s20, 0x3000
	s_addc_u32 s19, s21, 0
	global_load_dwordx4 v[216:219], v195, s[18:19]
	global_load_dwordx4 v[220:223], v195, s[18:19] offset:1024
	global_load_dwordx4 v[224:227], v195, s[18:19] offset:2048
	global_load_dwordx4 v[228:231], v195, s[18:19] offset:3072
	s_waitcnt vmcnt(16)
	v_pk_mul_f32 v[234:235], v[66:67], v[66:67]
	v_pk_mul_f32 v[236:237], v[68:69], v[68:69]
	v_pk_fma_f32 v[234:235], v[70:71], v[70:71], v[234:235]
	v_pk_fma_f32 v[236:237], v[72:73], v[72:73], v[236:237]
	v_pk_fma_f32 v[234:235], v[74:75], v[74:75], v[234:235]
	v_pk_fma_f32 v[236:237], v[76:77], v[76:77], v[236:237]
	v_pk_fma_f32 v[234:235], v[78:79], v[78:79], v[234:235]
	v_pk_fma_f32 v[236:237], v[80:81], v[80:81], v[236:237]
	v_pk_add_f32 v[234:235], v[234:235], v[236:237]
	v_add_f32_e32 v232, v234, v235
	v_pk_mul_f32 v[234:235], v[82:83], v[82:83]
	v_pk_mul_f32 v[236:237], v[84:85], v[84:85]
	v_pk_fma_f32 v[234:235], v[86:87], v[86:87], v[234:235]
	v_pk_fma_f32 v[236:237], v[88:89], v[88:89], v[236:237]
	v_pk_fma_f32 v[234:235], v[90:91], v[90:91], v[234:235]
	v_pk_fma_f32 v[236:237], v[92:93], v[92:93], v[236:237]
	v_pk_fma_f32 v[234:235], v[94:95], v[94:95], v[234:235]
	v_pk_fma_f32 v[236:237], v[96:97], v[96:97], v[236:237]
	v_pk_add_f32 v[234:235], v[234:235], v[236:237]
	v_add_f32_e32 v233, v234, v235
	s_nop 1
	v_add_f32_dpp v232, v232, v232 quad_perm:[1,0,3,2] row_mask:0xf bank_mask:0xf bound_ctrl:1
	s_nop 1
	v_add_f32_dpp v232, v232, v232 quad_perm:[2,3,0,1] row_mask:0xf bank_mask:0xf bound_ctrl:1
	s_nop 1
	v_add_f32_dpp v232, v232, v232 row_half_mirror row_mask:0xf bank_mask:0xf bound_ctrl:1
	s_nop 1
	v_add_f32_dpp v232, v232, v232 row_mirror row_mask:0xf bank_mask:0xf bound_ctrl:1
	s_nop 1
	v_readlane_b32 s18, v232, 0
	v_readlane_b32 s19, v232, 16
	v_readlane_b32 s27, v232, 32
	v_readlane_b32 s28, v232, 48
	s_nop 3
	v_mov_b32_e32 v234, s19
	v_mov_b32_e32 v235, s28
	v_add_f32_e32 v234, s18, v234
	v_add_f32_e32 v235, s27, v235
	v_add_f32_e32 v234, v234, v235
	v_mov_b32_e32 v235, 0x3a800000
	v_fma_f32 v234, v234, v235, v132
	v_rsq_f32_e32 v232, v234
	s_nop 1
	v_add_f32_dpp v233, v233, v233 quad_perm:[1,0,3,2] row_mask:0xf bank_mask:0xf bound_ctrl:1
	s_nop 1
	v_add_f32_dpp v233, v233, v233 quad_perm:[2,3,0,1] row_mask:0xf bank_mask:0xf bound_ctrl:1
	s_nop 1
	v_add_f32_dpp v233, v233, v233 row_half_mirror row_mask:0xf bank_mask:0xf bound_ctrl:1
	s_nop 1
	v_add_f32_dpp v233, v233, v233 row_mirror row_mask:0xf bank_mask:0xf bound_ctrl:1
	s_nop 1
	v_readlane_b32 s18, v233, 0
	v_readlane_b32 s19, v233, 16
	v_readlane_b32 s27, v233, 32
	v_readlane_b32 s28, v233, 48
	s_nop 3
	v_mov_b32_e32 v234, s19
	v_mov_b32_e32 v235, s28
	v_add_f32_e32 v234, s18, v234
	v_add_f32_e32 v235, s27, v235
	v_add_f32_e32 v234, v234, v235
	v_mov_b32_e32 v235, 0x3a800000
	v_fma_f32 v234, v234, v235, v132
	v_rsq_f32_e32 v233, v234
	s_load_dwordx2 s[18:19], s[0:1], 0x130
	s_lshl_b32 s27, s6, 3
	s_add_u32 s27, s27, s29
	s_lshl_b32 s27, s27, 11
	s_add_u32 s27, s27, 0x2b27800
	s_waitcnt lgkmcnt(0)
	s_add_u32 s18, s18, s27
	s_addc_u32 s19, s19, 0
	v_mul_f32_e32 v66, v232, v66
	v_mul_f32_e32 v67, v232, v67
	v_mul_f32_e32 v68, v232, v68
	v_mul_f32_e32 v69, v232, v69
	v_pk_mul_f32 v[66:67], v[66:67], v[134:135]
	v_pk_mul_f32 v[68:69], v[68:69], v[136:137]
	v_pk_add_f32 v[234:235], v[150:151], 1.0 op_sel_hi:[1,0]
	v_pk_add_f32 v[236:237], v[152:153], 1.0 op_sel_hi:[1,0]
	v_pk_fma_f32 v[66:67], v[66:67], v[234:235], v[166:167]
	v_pk_fma_f32 v[68:69], v[68:69], v[236:237], v[168:169]
	v_cvt_pk_bf16_f32 v66, v66, v67
	v_cvt_pk_bf16_f32 v67, v68, v69
	global_store_dwordx2 v241, v[66:67], s[18:19] offset:0
	v_mul_f32_e32 v70, v232, v70
	v_mul_f32_e32 v71, v232, v71
	v_mul_f32_e32 v72, v232, v72
	v_mul_f32_e32 v73, v232, v73
	v_pk_mul_f32 v[70:71], v[70:71], v[138:139]
	v_pk_mul_f32 v[72:73], v[72:73], v[140:141]
	v_pk_add_f32 v[234:235], v[154:155], 1.0 op_sel_hi:[1,0]
	v_pk_add_f32 v[236:237], v[156:157], 1.0 op_sel_hi:[1,0]
	v_pk_fma_f32 v[70:71], v[70:71], v[234:235], v[170:171]
	v_pk_fma_f32 v[72:73], v[72:73], v[236:237], v[172:173]
	v_cvt_pk_bf16_f32 v70, v70, v71
	v_cvt_pk_bf16_f32 v71, v72, v73
	global_store_dwordx2 v241, v[70:71], s[18:19] offset:512
	v_mul_f32_e32 v74, v232, v74
	v_mul_f32_e32 v75, v232, v75
	v_mul_f32_e32 v76, v232, v76
	v_mul_f32_e32 v77, v232, v77
	v_pk_mul_f32 v[74:75], v[74:75], v[142:143]
	v_pk_mul_f32 v[76:77], v[76:77], v[144:145]
	v_pk_add_f32 v[234:235], v[158:159], 1.0 op_sel_hi:[1,0]
	v_pk_add_f32 v[236:237], v[160:161], 1.0 op_sel_hi:[1,0]
	v_pk_fma_f32 v[74:75], v[74:75], v[234:235], v[174:175]
	v_pk_fma_f32 v[76:77], v[76:77], v[236:237], v[176:177]
	v_cvt_pk_bf16_f32 v74, v74, v75
	v_cvt_pk_bf16_f32 v75, v76, v77
	global_store_dwordx2 v241, v[74:75], s[18:19] offset:1024
	v_mul_f32_e32 v78, v232, v78
	v_mul_f32_e32 v79, v232, v79
	v_mul_f32_e32 v80, v232, v80
	v_mul_f32_e32 v81, v232, v81
	v_pk_mul_f32 v[78:79], v[78:79], v[146:147]
	v_pk_mul_f32 v[80:81], v[80:81], v[148:149]
	v_pk_add_f32 v[234:235], v[162:163], 1.0 op_sel_hi:[1,0]
	v_pk_add_f32 v[236:237], v[164:165], 1.0 op_sel_hi:[1,0]
	v_pk_fma_f32 v[78:79], v[78:79], v[234:235], v[178:179]
	v_pk_fma_f32 v[80:81], v[80:81], v[236:237], v[180:181]
	v_cvt_pk_bf16_f32 v78, v78, v79
	v_cvt_pk_bf16_f32 v79, v80, v81
	global_store_dwordx2 v241, v[78:79], s[18:19] offset:1536
	v_mul_f32_e32 v82, v233, v82
	v_mul_f32_e32 v83, v233, v83
	v_mul_f32_e32 v84, v233, v84
	v_mul_f32_e32 v85, v233, v85
	v_pk_mul_f32 v[82:83], v[82:83], v[134:135]
	v_pk_mul_f32 v[84:85], v[84:85], v[136:137]
	v_pk_add_f32 v[234:235], v[150:151], 1.0 op_sel_hi:[1,0]
	v_pk_add_f32 v[236:237], v[152:153], 1.0 op_sel_hi:[1,0]
	v_pk_fma_f32 v[82:83], v[82:83], v[234:235], v[166:167]
	v_pk_fma_f32 v[84:85], v[84:85], v[236:237], v[168:169]
	v_cvt_pk_bf16_f32 v82, v82, v83
	v_cvt_pk_bf16_f32 v83, v84, v85
	global_store_dwordx2 v241, v[82:83], s[18:19] offset:2048
	v_mul_f32_e32 v86, v233, v86
	v_mul_f32_e32 v87, v233, v87
	v_mul_f32_e32 v88, v233, v88
	v_mul_f32_e32 v89, v233, v89
	v_pk_mul_f32 v[86:87], v[86:87], v[138:139]
	v_pk_mul_f32 v[88:89], v[88:89], v[140:141]
	v_pk_add_f32 v[234:235], v[154:155], 1.0 op_sel_hi:[1,0]
	v_pk_add_f32 v[236:237], v[156:157], 1.0 op_sel_hi:[1,0]
	v_pk_fma_f32 v[86:87], v[86:87], v[234:235], v[170:171]
	v_pk_fma_f32 v[88:89], v[88:89], v[236:237], v[172:173]
	v_cvt_pk_bf16_f32 v86, v86, v87
	v_cvt_pk_bf16_f32 v87, v88, v89
	global_store_dwordx2 v241, v[86:87], s[18:19] offset:2560
	v_mul_f32_e32 v90, v233, v90
	v_mul_f32_e32 v91, v233, v91
	v_mul_f32_e32 v92, v233, v92
	v_mul_f32_e32 v93, v233, v93
	v_pk_mul_f32 v[90:91], v[90:91], v[142:143]
	v_pk_mul_f32 v[92:93], v[92:93], v[144:145]
	v_pk_add_f32 v[234:235], v[158:159], 1.0 op_sel_hi:[1,0]
	v_pk_add_f32 v[236:237], v[160:161], 1.0 op_sel_hi:[1,0]
	v_pk_fma_f32 v[90:91], v[90:91], v[234:235], v[174:175]
	v_pk_fma_f32 v[92:93], v[92:93], v[236:237], v[176:177]
	v_cvt_pk_bf16_f32 v90, v90, v91
	v_cvt_pk_bf16_f32 v91, v92, v93
	global_store_dwordx2 v241, v[90:91], s[18:19] offset:3072
	v_mul_f32_e32 v94, v233, v94
	v_mul_f32_e32 v95, v233, v95
	v_mul_f32_e32 v96, v233, v96
	v_mul_f32_e32 v97, v233, v97
	v_pk_mul_f32 v[94:95], v[94:95], v[146:147]
	v_pk_mul_f32 v[96:97], v[96:97], v[148:149]
	v_pk_add_f32 v[234:235], v[162:163], 1.0 op_sel_hi:[1,0]
	v_pk_add_f32 v[236:237], v[164:165], 1.0 op_sel_hi:[1,0]
	v_pk_fma_f32 v[94:95], v[94:95], v[234:235], v[178:179]
	v_pk_fma_f32 v[96:97], v[96:97], v[236:237], v[180:181]
	v_cvt_pk_bf16_f32 v94, v94, v95
	v_cvt_pk_bf16_f32 v95, v96, v97
	global_store_dwordx2 v241, v[94:95], s[18:19] offset:3584
	s_cmp_le_u32 s7, 3
	s_cbranch_scc1 .Lnb1_alldone
	s_mul_i32 s6, s42, 3
	s_add_u32 s6, s6, s25
	s_waitcnt vmcnt(8)
	v_pk_mul_f32 v[234:235], v[98:99], v[98:99]
	v_pk_mul_f32 v[236:237], v[100:101], v[100:101]
	v_pk_fma_f32 v[234:235], v[102:103], v[102:103], v[234:235]
	v_pk_fma_f32 v[236:237], v[104:105], v[104:105], v[236:237]
	v_pk_fma_f32 v[234:235], v[106:107], v[106:107], v[234:235]
	v_pk_fma_f32 v[236:237], v[108:109], v[108:109], v[236:237]
	v_pk_fma_f32 v[234:235], v[110:111], v[110:111], v[234:235]
	v_pk_fma_f32 v[236:237], v[112:113], v[112:113], v[236:237]
	v_pk_add_f32 v[234:235], v[234:235], v[236:237]
	v_add_f32_e32 v232, v234, v235
	v_pk_mul_f32 v[234:235], v[114:115], v[114:115]
	v_pk_mul_f32 v[236:237], v[116:117], v[116:117]
	v_pk_fma_f32 v[234:235], v[118:119], v[118:119], v[234:235]
	v_pk_fma_f32 v[236:237], v[120:121], v[120:121], v[236:237]
	v_pk_fma_f32 v[234:235], v[122:123], v[122:123], v[234:235]
	v_pk_fma_f32 v[236:237], v[124:125], v[124:125], v[236:237]
	v_pk_fma_f32 v[234:235], v[126:127], v[126:127], v[234:235]
	v_pk_fma_f32 v[236:237], v[128:129], v[128:129], v[236:237]
	v_pk_add_f32 v[234:235], v[234:235], v[236:237]
	v_add_f32_e32 v233, v234, v235
	s_nop 1
	v_add_f32_dpp v232, v232, v232 quad_perm:[1,0,3,2] row_mask:0xf bank_mask:0xf bound_ctrl:1
	s_nop 1
	v_add_f32_dpp v232, v232, v232 quad_perm:[2,3,0,1] row_mask:0xf bank_mask:0xf bound_ctrl:1
	s_nop 1
	v_add_f32_dpp v232, v232, v232 row_half_mirror row_mask:0xf bank_mask:0xf bound_ctrl:1
	s_nop 1
	v_add_f32_dpp v232, v232, v232 row_mirror row_mask:0xf bank_mask:0xf bound_ctrl:1
	s_nop 1
	v_readlane_b32 s18, v232, 0
	v_readlane_b32 s19, v232, 16
	v_readlane_b32 s27, v232, 32
	v_readlane_b32 s28, v232, 48
	s_nop 3
	v_mov_b32_e32 v234, s19
	v_mov_b32_e32 v235, s28
	v_add_f32_e32 v234, s18, v234
	v_add_f32_e32 v235, s27, v235
	v_add_f32_e32 v234, v234, v235
	v_mov_b32_e32 v235, 0x3a800000
	v_fma_f32 v234, v234, v235, v132
	v_rsq_f32_e32 v232, v234
	s_nop 1
	v_add_f32_dpp v233, v233, v233 quad_perm:[1,0,3,2] row_mask:0xf bank_mask:0xf bound_ctrl:1
	s_nop 1
	v_add_f32_dpp v233, v233, v233 quad_perm:[2,3,0,1] row_mask:0xf bank_mask:0xf bound_ctrl:1
	s_nop 1
	v_add_f32_dpp v233, v233, v233 row_half_mirror row_mask:0xf bank_mask:0xf bound_ctrl:1
	s_nop 1
	v_add_f32_dpp v233, v233, v233 row_mirror row_mask:0xf bank_mask:0xf bound_ctrl:1
	s_nop 1
	v_readlane_b32 s18, v233, 0
	v_readlane_b32 s19, v233, 16
	v_readlane_b32 s27, v233, 32
	v_readlane_b32 s28, v233, 48
	s_nop 3
	v_mov_b32_e32 v234, s19
	v_mov_b32_e32 v235, s28
	v_add_f32_e32 v234, s18, v234
	v_add_f32_e32 v235, s27, v235
	v_add_f32_e32 v234, v234, v235
	v_mov_b32_e32 v235, 0x3a800000
	v_fma_f32 v234, v234, v235, v132
	v_rsq_f32_e32 v233, v234
	s_load_dwordx2 s[18:19], s[0:1], 0x130
	s_lshl_b32 s27, s6, 3
	s_add_u32 s27, s27, s29
	s_lshl_b32 s27, s27, 11
	s_add_u32 s27, s27, 0x2b27800
	s_waitcnt lgkmcnt(0)
	s_add_u32 s18, s18, s27
	s_addc_u32 s19, s19, 0
	v_mul_f32_e32 v98, v232, v98
	v_mul_f32_e32 v99, v232, v99
	v_mul_f32_e32 v100, v232, v100
	v_mul_f32_e32 v101, v232, v101
	v_pk_mul_f32 v[98:99], v[98:99], v[134:135]
	v_pk_mul_f32 v[100:101], v[100:101], v[136:137]
	v_pk_add_f32 v[234:235], v[196:197], 1.0 op_sel_hi:[1,0]
	v_pk_add_f32 v[236:237], v[198:199], 1.0 op_sel_hi:[1,0]
	v_pk_fma_f32 v[98:99], v[98:99], v[234:235], v[216:217]
	v_pk_fma_f32 v[100:101], v[100:101], v[236:237], v[218:219]
	v_cvt_pk_bf16_f32 v98, v98, v99
	v_cvt_pk_bf16_f32 v99, v100, v101
	global_store_dwordx2 v241, v[98:99], s[18:19] offset:0
	v_mul_f32_e32 v102, v232, v102
	v_mul_f32_e32 v103, v232, v103
	v_mul_f32_e32 v104, v232, v104
	v_mul_f32_e32 v105, v232, v105
	v_pk_mul_f32 v[102:103], v[102:103], v[138:139]
	v_pk_mul_f32 v[104:105], v[104:105], v[140:141]
	v_pk_add_f32 v[234:235], v[200:201], 1.0 op_sel_hi:[1,0]
	v_pk_add_f32 v[236:237], v[202:203], 1.0 op_sel_hi:[1,0]
	v_pk_fma_f32 v[102:103], v[102:103], v[234:235], v[220:221]
	v_pk_fma_f32 v[104:105], v[104:105], v[236:237], v[222:223]
	v_cvt_pk_bf16_f32 v102, v102, v103
	v_cvt_pk_bf16_f32 v103, v104, v105
	global_store_dwordx2 v241, v[102:103], s[18:19] offset:512
	v_mul_f32_e32 v106, v232, v106
	v_mul_f32_e32 v107, v232, v107
	v_mul_f32_e32 v108, v232, v108
	v_mul_f32_e32 v109, v232, v109
	v_pk_mul_f32 v[106:107], v[106:107], v[142:143]
	v_pk_mul_f32 v[108:109], v[108:109], v[144:145]
	v_pk_add_f32 v[234:235], v[204:205], 1.0 op_sel_hi:[1,0]
	v_pk_add_f32 v[236:237], v[206:207], 1.0 op_sel_hi:[1,0]
	v_pk_fma_f32 v[106:107], v[106:107], v[234:235], v[224:225]
	v_pk_fma_f32 v[108:109], v[108:109], v[236:237], v[226:227]
	v_cvt_pk_bf16_f32 v106, v106, v107
	v_cvt_pk_bf16_f32 v107, v108, v109
	global_store_dwordx2 v241, v[106:107], s[18:19] offset:1024
	v_mul_f32_e32 v110, v232, v110
	v_mul_f32_e32 v111, v232, v111
	v_mul_f32_e32 v112, v232, v112
	v_mul_f32_e32 v113, v232, v113
	v_pk_mul_f32 v[110:111], v[110:111], v[146:147]
	v_pk_mul_f32 v[112:113], v[112:113], v[148:149]
	v_pk_add_f32 v[234:235], v[212:213], 1.0 op_sel_hi:[1,0]
	v_pk_add_f32 v[236:237], v[214:215], 1.0 op_sel_hi:[1,0]
	v_pk_fma_f32 v[110:111], v[110:111], v[234:235], v[228:229]
	v_pk_fma_f32 v[112:113], v[112:113], v[236:237], v[230:231]
	v_cvt_pk_bf16_f32 v110, v110, v111
	v_cvt_pk_bf16_f32 v111, v112, v113
	global_store_dwordx2 v241, v[110:111], s[18:19] offset:1536
	v_mul_f32_e32 v114, v233, v114
	v_mul_f32_e32 v115, v233, v115
	v_mul_f32_e32 v116, v233, v116
	v_mul_f32_e32 v117, v233, v117
	v_pk_mul_f32 v[114:115], v[114:115], v[134:135]
	v_pk_mul_f32 v[116:117], v[116:117], v[136:137]
	v_pk_add_f32 v[234:235], v[196:197], 1.0 op_sel_hi:[1,0]
	v_pk_add_f32 v[236:237], v[198:199], 1.0 op_sel_hi:[1,0]
	v_pk_fma_f32 v[114:115], v[114:115], v[234:235], v[216:217]
	v_pk_fma_f32 v[116:117], v[116:117], v[236:237], v[218:219]
	v_cvt_pk_bf16_f32 v114, v114, v115
	v_cvt_pk_bf16_f32 v115, v116, v117
	global_store_dwordx2 v241, v[114:115], s[18:19] offset:2048
	v_mul_f32_e32 v118, v233, v118
	v_mul_f32_e32 v119, v233, v119
	v_mul_f32_e32 v120, v233, v120
	v_mul_f32_e32 v121, v233, v121
	v_pk_mul_f32 v[118:119], v[118:119], v[138:139]
	v_pk_mul_f32 v[120:121], v[120:121], v[140:141]
	v_pk_add_f32 v[234:235], v[200:201], 1.0 op_sel_hi:[1,0]
	v_pk_add_f32 v[236:237], v[202:203], 1.0 op_sel_hi:[1,0]
	v_pk_fma_f32 v[118:119], v[118:119], v[234:235], v[220:221]
	v_pk_fma_f32 v[120:121], v[120:121], v[236:237], v[222:223]
	v_cvt_pk_bf16_f32 v118, v118, v119
	v_cvt_pk_bf16_f32 v119, v120, v121
	global_store_dwordx2 v241, v[118:119], s[18:19] offset:2560
	v_mul_f32_e32 v122, v233, v122
	v_mul_f32_e32 v123, v233, v123
	v_mul_f32_e32 v124, v233, v124
	v_mul_f32_e32 v125, v233, v125
	v_pk_mul_f32 v[122:123], v[122:123], v[142:143]
	v_pk_mul_f32 v[124:125], v[124:125], v[144:145]
	v_pk_add_f32 v[234:235], v[204:205], 1.0 op_sel_hi:[1,0]
	v_pk_add_f32 v[236:237], v[206:207], 1.0 op_sel_hi:[1,0]
	v_pk_fma_f32 v[122:123], v[122:123], v[234:235], v[224:225]
	v_pk_fma_f32 v[124:125], v[124:125], v[236:237], v[226:227]
	v_cvt_pk_bf16_f32 v122, v122, v123
	v_cvt_pk_bf16_f32 v123, v124, v125
	global_store_dwordx2 v241, v[122:123], s[18:19] offset:3072
	v_mul_f32_e32 v126, v233, v126
	v_mul_f32_e32 v127, v233, v127
	v_mul_f32_e32 v128, v233, v128
	v_mul_f32_e32 v129, v233, v129
	v_pk_mul_f32 v[126:127], v[126:127], v[146:147]
	v_pk_mul_f32 v[128:129], v[128:129], v[148:149]
	v_pk_add_f32 v[234:235], v[212:213], 1.0 op_sel_hi:[1,0]
	v_pk_add_f32 v[236:237], v[214:215], 1.0 op_sel_hi:[1,0]
	v_pk_fma_f32 v[126:127], v[126:127], v[234:235], v[228:229]
	v_pk_fma_f32 v[128:129], v[128:129], v[236:237], v[230:231]
	v_cvt_pk_bf16_f32 v126, v126, v127
	v_cvt_pk_bf16_f32 v127, v128, v129
	global_store_dwordx2 v241, v[126:127], s[18:19] offset:3584
.Lnb1_alldone:
	s_sub_u32 s7, s7, 1
	s_mul_i32 s7, s7, s42
	s_add_u32 s25, s25, s7
	s_add_u32 s26, s25, s42
	s_cmp_lt_u32 s26, 2048
	s_cbranch_scc0 .Lnb1_exit
	s_mov_b32 s25, s26
	s_branch .Lnb1_again
.Lnb1_exit:
.LBB0_50:
	s_mov_b64 s[4:5], 0
.LBB0_51:
	s_andn2_b64 vcc, exec, s[4:5]
	s_cbranch_vccnz .LBB0_90
	v_readlane_b32 s3, v239, 47
	s_cmp_gt_i32 s3, 5
	s_mov_b64 s[4:5], -1
	s_cbranch_scc0 .LBB0_67
	s_andn2_b64 vcc, exec, s[92:93]
	s_cbranch_vccnz .LBB0_60
	s_andn2_b64 vcc, exec, s[94:95]
	s_cbranch_vccnz .LBB0_59
	s_load_dwordx2 s[4:5], s[0:1], 0x130
	s_mov_b32 s21, s66
	s_waitcnt lgkmcnt(0)
	s_add_u32 s3, s4, 0x4b27800
	s_addc_u32 s18, s5, 0
	s_add_u32 s19, s4, 0x1927800
	s_addc_u32 s20, s5, 0
	s_add_i32 s6, s30, 8
	s_cmp_lt_u32 s6, 19
	s_cselect_b64 vcc, -1, 0
	s_add_u32 s8, s4, 0x1927880
	s_addc_u32 s9, s5, 0
	s_add_u32 s10, s4, 0x4b27880
	s_addc_u32 s11, s5, 0

.LBB0_927:
	s_mov_b32 s25, s24
.Lnb0_again:
	v_and_b32_e32 v0, 63, v133
	v_lshrrev_b32_e32 v234, 6, v133
	v_lshlrev_b32_e32 v195, 4, v0
	v_readfirstlane_b32 s29, v234
	v_add_u32_e32 v240, 0x1000, v195
	v_lshlrev_b32_e32 v241, 3, v0
	s_lshl_b32 s29, s29, 1
	s_load_dwordx2 s[20:21], s[0:1], 0x60
	s_lshl_b32 s26, s62, 12
	s_waitcnt lgkmcnt(0)
	s_add_u32 s20, s20, s26
	s_addc_u32 s21, s21, 0
	global_load_dwordx4 v[134:137], v195, s[20:21]
	global_load_dwordx4 v[138:141], v195, s[20:21] offset:1024
	global_load_dwordx4 v[142:145], v195, s[20:21] offset:2048
	global_load_dwordx4 v[146:149], v195, s[20:21] offset:3072
	s_mov_b32 s26, s25
	s_mov_b32 s7, 0
	s_cmp_ge_u32 s26, 2048
	s_cbranch_scc1 .Lnb0_xdone
	s_lshl_b32 s27, s26, 3
	s_add_u32 s27, s27, s29
	s_cmp_eq_u32 s62, 0
	s_cbranch_scc1 .Lnb0_x0_l0
	s_load_dwordx2 s[20:21], s[0:1], 0x128
	s_branch .Lnb0_x0_go
.Lnb0_x0_l0:
	s_lshr_b32 s28, s27, 13
	s_lshl_b32 s28, s28, 3
	s_load_dwordx2 s[20:21], s[0:1], s28
	s_and_b32 s27, s27, 0x1fff
.Lnb0_x0_go:
	s_lshl_b32 s27, s27, 12
	s_waitcnt lgkmcnt(0)
	s_add_u32 s20, s20, s27
	s_addc_u32 s21, s21, 0
	global_load_dwordx4 v[2:5], v195, s[20:21]
	global_load_dwordx4 v[6:9], v195, s[20:21] offset:1024
	global_load_dwordx4 v[10:13], v195, s[20:21] offset:2048
	global_load_dwordx4 v[14:17], v195, s[20:21] offset:3072
	global_load_dwordx4 v[18:21], v240, s[20:21]
	global_load_dwordx4 v[22:25], v240, s[20:21] offset:1024
	global_load_dwordx4 v[26:29], v240, s[20:21] offset:2048
	global_load_dwordx4 v[30:33], v240, s[20:21] offset:3072
	s_add_u32 s7, s7, 1
	s_add_u32 s26, s26, s42
	s_cmp_ge_u32 s26, 2048
	s_cbranch_scc1 .Lnb0_xdone
	s_lshl_b32 s27, s26, 3
	s_add_u32 s27, s27, s29
	s_cmp_eq_u32 s62, 0
	s_cbranch_scc1 .Lnb0_x1_l0
	s_load_dwordx2 s[20:21], s[0:1], 0x128
	s_branch .Lnb0_x1_go

.Lnb0_x1_go:
	s_lshl_b32 s27, s27, 12
	s_waitcnt lgkmcnt(0)
	s_add_u32 s20, s20, s27
	s_addc_u32 s21, s21, 0
	global_load_dwordx4 v[34:37], v195, s[20:21]
	global_load_dwordx4 v[38:41], v195, s[20:21] offset:1024
	global_load_dwordx4 v[42:45], v195, s[20:21] offset:2048
	global_load_dwordx4 v[46:49], v195, s[20:21] offset:3072
	global_load_dwordx4 v[50:53], v240, s[20:21]
	global_load_dwordx4 v[54:57], v240, s[20:21] offset:1024
	global_load_dwordx4 v[58:61], v240, s[20:21] offset:2048
	global_load_dwordx4 v[62:65], v240, s[20:21] offset:3072
	s_add_u32 s7, s7, 1
	s_add_u32 s26, s26, s42
	s_cmp_ge_u32 s26, 2048
	s_cbranch_scc1 .Lnb0_xdone
	s_lshl_b32 s27, s26, 3
	s_add_u32 s27, s27, s29
	s_cmp_eq_u32 s62, 0
	s_cbranch_scc1 .Lnb0_x2_l0
	s_load_dwordx2 s[20:21], s[0:1], 0x128
	s_branch .Lnb0_x2_go

.Lnb0_x2_go:
	s_lshl_b32 s27, s27, 12
	s_waitcnt lgkmcnt(0)
	s_add_u32 s20, s20, s27
	s_addc_u32 s21, s21, 0
	global_load_dwordx4 v[66:69], v195, s[20:21]
	global_load_dwordx4 v[70:73], v195, s[20:21] offset:1024
	global_load_dwordx4 v[74:77], v195, s[20:21] offset:2048
	global_load_dwordx4 v[78:81], v195, s[20:21] offset:3072
	global_load_dwordx4 v[82:85], v240, s[20:21]
	global_load_dwordx4 v[86:89], v240, s[20:21] offset:1024
	global_load_dwordx4 v[90:93], v240, s[20:21] offset:2048
	global_load_dwordx4 v[94:97], v240, s[20:21] offset:3072
	s_add_u32 s7, s7, 1
	s_add_u32 s26, s26, s42
	s_cmp_ge_u32 s26, 2048
	s_cbranch_scc1 .Lnb0_xdone
	s_lshl_b32 s27, s26, 3
	s_add_u32 s27, s27, s29
	s_cmp_eq_u32 s62, 0
	s_cbranch_scc1 .Lnb0_x3_l0
	s_load_dwordx2 s[20:21], s[0:1], 0x128
	s_branch .Lnb0_x3_go

.Lnb0_x3_go:
	s_lshl_b32 s27, s27, 12
	s_waitcnt lgkmcnt(0)
	s_add_u32 s20, s20, s27
	s_addc_u32 s21, s21, 0
	global_load_dwordx4 v[98:101], v195, s[20:21]
	global_load_dwordx4 v[102:105], v195, s[20:21] offset:1024
	global_load_dwordx4 v[106:109], v195, s[20:21] offset:2048
	global_load_dwordx4 v[110:113], v195, s[20:21] offset:3072
	global_load_dwordx4 v[114:117], v240, s[20:21]
	global_load_dwordx4 v[118:121], v240, s[20:21] offset:1024
	global_load_dwordx4 v[122:125], v240, s[20:21] offset:2048
	global_load_dwordx4 v[126:129], v240, s[20:21] offset:3072
	s_add_u32 s7, s7, 1
	s_add_u32 s26, s26, s42
.Lnb0_xdone:
	s_mov_b32 s26, s25
	s_load_dwordx2 s[20:21], s[0:1], 0x130
	s_lshr_b32 s27, s26, 9
	s_max_u32 s27, s27, 1
	s_sub_u32 s27, s27, 1
	s_mul_i32 s28, s62, 3
	s_add_u32 s27, s27, s28
	s_mul_i32 s27, s27, 24576
	s_waitcnt lgkmcnt(0)
	s_add_u32 s20, s20, s27
	s_addc_u32 s21, s21, 0
	s_add_u32 s18, s20, 0x1000
	s_addc_u32 s19, s21, 0
	global_load_dwordx4 v[150:153], v195, s[18:19]
	global_load_dwordx4 v[154:157], v195, s[18:19] offset:1024
	global_load_dwordx4 v[158:161], v195, s[18:19] offset:2048
	global_load_dwordx4 v[162:165], v195, s[18:19] offset:3072
	global_load_dwordx4 v[166:169], v195, s[20:21]
	global_load_dwordx4 v[170:173], v195, s[20:21] offset:1024
	global_load_dwordx4 v[174:177], v195, s[20:21] offset:2048
	global_load_dwordx4 v[178:181], v195, s[20:21] offset:3072
	s_mul_i32 s6, s42, 0
	s_add_u32 s6, s6, s25
	s_add_u32 s26, s6, s42
	s_min_u32 s26, s26, 2047
	s_load_dwordx2 s[20:21], s[0:1], 0x130
	s_lshr_b32 s27, s26, 9
	s_max_u32 s27, s27, 1
	s_sub_u32 s27, s27, 1
	s_mul_i32 s28, s62, 3
	s_add_u32 s27, s27, s28
	s_mul_i32 s27, s27, 24576
	s_waitcnt lgkmcnt(0)
	s_add_u32 s20, s20, s27
	s_addc_u32 s21, s21, 0
	s_add_u32 s18, s20, 0x1000
	s_addc_u32 s19, s21, 0
	global_load_dwordx4 v[196:199], v195, s[18:19]
	global_load_dwordx4 v[200:203], v195, s[18:19] offset:1024
	global_load_dwordx4 v[204:207], v195, s[18:19] offset:2048
	global_load_dwordx4 v[212:215], v195, s[18:19] offset:3072
	global_load_dwordx4 v[216:219], v195, s[20:21]
	global_load_dwordx4 v[220:223], v195, s[20:21] offset:1024
	global_load_dwordx4 v[224:227], v195, s[20:21] offset:2048
	global_load_dwordx4 v[228:231], v195, s[20:21] offset:3072
	s_waitcnt vmcnt(8)
	v_pk_mul_f32 v[234:235], v[2:3], v[2:3]
	v_pk_mul_f32 v[236:237], v[4:5], v[4:5]
	v_pk_fma_f32 v[234:235], v[6:7], v[6:7], v[234:235]
	v_pk_fma_f32 v[236:237], v[8:9], v[8:9], v[236:237]
	v_pk_fma_f32 v[234:235], v[10:11], v[10:11], v[234:235]
	v_pk_fma_f32 v[236:237], v[12:13], v[12:13], v[236:237]
	v_pk_fma_f32 v[234:235], v[14:15], v[14:15], v[234:235]
	v_pk_fma_f32 v[236:237], v[16:17], v[16:17], v[236:237]
	v_pk_add_f32 v[234:235], v[234:235], v[236:237]
	v_add_f32_e32 v232, v234, v235
	v_pk_mul_f32 v[234:235], v[18:19], v[18:19]
	v_pk_mul_f32 v[236:237], v[20:21], v[20:21]
	v_pk_fma_f32 v[234:235], v[22:23], v[22:23], v[234:235]
	v_pk_fma_f32 v[236:237], v[24:25], v[24:25], v[236:237]
	v_pk_fma_f32 v[234:235], v[26:27], v[26:27], v[234:235]
	v_pk_fma_f32 v[236:237], v[28:29], v[28:29], v[236:237]
	v_pk_fma_f32 v[234:235], v[30:31], v[30:31], v[234:235]
	v_pk_fma_f32 v[236:237], v[32:33], v[32:33], v[236:237]
	v_pk_add_f32 v[234:235], v[234:235], v[236:237]
	v_add_f32_e32 v233, v234, v235
	s_nop 1
	v_add_f32_dpp v232, v232, v232 quad_perm:[1,0,3,2] row_mask:0xf bank_mask:0xf bound_ctrl:1
	s_nop 1
	v_add_f32_dpp v232, v232, v232 quad_perm:[2,3,0,1] row_mask:0xf bank_mask:0xf bound_ctrl:1
	s_nop 1
	v_add_f32_dpp v232, v232, v232 row_half_mirror row_mask:0xf bank_mask:0xf bound_ctrl:1
	s_nop 1
	v_add_f32_dpp v232, v232, v232 row_mirror row_mask:0xf bank_mask:0xf bound_ctrl:1
	s_nop 1
	v_readlane_b32 s18, v232, 0
	v_readlane_b32 s19, v232, 16
	v_readlane_b32 s27, v232, 32
	v_readlane_b32 s28, v232, 48
	s_nop 3
	v_mov_b32_e32 v234, s19
	v_mov_b32_e32 v235, s28
	v_add_f32_e32 v234, s18, v234
	v_add_f32_e32 v235, s27, v235
	v_add_f32_e32 v234, v234, v235
	v_mov_b32_e32 v235, 0x3a800000
	v_fma_f32 v234, v234, v235, v132
	v_rsq_f32_e32 v232, v234
	s_nop 1
	v_add_f32_dpp v233, v233, v233 quad_perm:[1,0,3,2] row_mask:0xf bank_mask:0xf bound_ctrl:1
	s_nop 1
	v_add_f32_dpp v233, v233, v233 quad_perm:[2,3,0,1] row_mask:0xf bank_mask:0xf bound_ctrl:1
	s_nop 1
	v_add_f32_dpp v233, v233, v233 row_half_mirror row_mask:0xf bank_mask:0xf bound_ctrl:1
	s_nop 1
	v_add_f32_dpp v233, v233, v233 row_mirror row_mask:0xf bank_mask:0xf bound_ctrl:1
	s_nop 1
	v_readlane_b32 s18, v233, 0
	v_readlane_b32 s19, v233, 16
	v_readlane_b32 s27, v233, 32
	v_readlane_b32 s28, v233, 48
	s_nop 3
	v_mov_b32_e32 v234, s19
	v_mov_b32_e32 v235, s28
	v_add_f32_e32 v234, s18, v234
	v_add_f32_e32 v235, s27, v235
	v_add_f32_e32 v234, v234, v235
	v_mov_b32_e32 v235, 0x3a800000
	v_fma_f32 v234, v234, v235, v132
	v_rsq_f32_e32 v233, v234
	s_load_dwordx2 s[18:19], s[0:1], 0x130
	s_lshl_b32 s27, s6, 3
	s_add_u32 s27, s27, s29
	s_lshl_b32 s27, s27, 11
	s_add_u32 s27, s27, 0x2b27800
	s_waitcnt lgkmcnt(0)
	s_add_u32 s18, s18, s27
	s_addc_u32 s19, s19, 0
	v_mul_f32_e32 v2, v232, v2
	v_mul_f32_e32 v3, v232, v3
	v_mul_f32_e32 v4, v232, v4
	v_mul_f32_e32 v5, v232, v5
	v_pk_mul_f32 v[2:3], v[2:3], v[134:135]
	v_pk_mul_f32 v[4:5], v[4:5], v[136:137]
	v_pk_add_f32 v[234:235], v[150:151], 1.0 op_sel_hi:[1,0]
	v_pk_add_f32 v[236:237], v[152:153], 1.0 op_sel_hi:[1,0]
	v_pk_fma_f32 v[2:3], v[2:3], v[234:235], v[166:167]
	v_pk_fma_f32 v[4:5], v[4:5], v[236:237], v[168:169]
	v_cvt_pk_bf16_f32 v2, v2, v3
	v_cvt_pk_bf16_f32 v3, v4, v5
	global_store_dwordx2 v241, v[2:3], s[18:19] offset:0
	v_mul_f32_e32 v6, v232, v6
	v_mul_f32_e32 v7, v232, v7
	v_mul_f32_e32 v8, v232, v8
	v_mul_f32_e32 v9, v232, v9
	v_pk_mul_f32 v[6:7], v[6:7], v[138:139]
	v_pk_mul_f32 v[8:9], v[8:9], v[140:141]
	v_pk_add_f32 v[234:235], v[154:155], 1.0 op_sel_hi:[1,0]
	v_pk_add_f32 v[236:237], v[156:157], 1.0 op_sel_hi:[1,0]
	v_pk_fma_f32 v[6:7], v[6:7], v[234:235], v[170:171]
	v_pk_fma_f32 v[8:9], v[8:9], v[236:237], v[172:173]
	v_cvt_pk_bf16_f32 v6, v6, v7
	v_cvt_pk_bf16_f32 v7, v8, v9
	global_store_dwordx2 v241, v[6:7], s[18:19] offset:512
	v_mul_f32_e32 v10, v232, v10
	v_mul_f32_e32 v11, v232, v11
	v_mul_f32_e32 v12, v232, v12
	v_mul_f32_e32 v13, v232, v13
	v_pk_mul_f32 v[10:11], v[10:11], v[142:143]
	v_pk_mul_f32 v[12:13], v[12:13], v[144:145]
	v_pk_add_f32 v[234:235], v[158:159], 1.0 op_sel_hi:[1,0]
	v_pk_add_f32 v[236:237], v[160:161], 1.0 op_sel_hi:[1,0]
	v_pk_fma_f32 v[10:11], v[10:11], v[234:235], v[174:175]
	v_pk_fma_f32 v[12:13], v[12:13], v[236:237], v[176:177]
	v_cvt_pk_bf16_f32 v10, v10, v11
	v_cvt_pk_bf16_f32 v11, v12, v13
	global_store_dwordx2 v241, v[10:11], s[18:19] offset:1024
	v_mul_f32_e32 v14, v232, v14
	v_mul_f32_e32 v15, v232, v15
	v_mul_f32_e32 v16, v232, v16
	v_mul_f32_e32 v17, v232, v17
	v_pk_mul_f32 v[14:15], v[14:15], v[146:147]
	v_pk_mul_f32 v[16:17], v[16:17], v[148:149]
	v_pk_add_f32 v[234:235], v[162:163], 1.0 op_sel_hi:[1,0]
	v_pk_add_f32 v[236:237], v[164:165], 1.0 op_sel_hi:[1,0]
	v_pk_fma_f32 v[14:15], v[14:15], v[234:235], v[178:179]
	v_pk_fma_f32 v[16:17], v[16:17], v[236:237], v[180:181]
	v_cvt_pk_bf16_f32 v14, v14, v15
	v_cvt_pk_bf16_f32 v15, v16, v17
	global_store_dwordx2 v241, v[14:15], s[18:19] offset:1536
	v_mul_f32_e32 v18, v233, v18
	v_mul_f32_e32 v19, v233, v19
	v_mul_f32_e32 v20, v233, v20
	v_mul_f32_e32 v21, v233, v21
	v_pk_mul_f32 v[18:19], v[18:19], v[134:135]
	v_pk_mul_f32 v[20:21], v[20:21], v[136:137]
	v_pk_add_f32 v[234:235], v[150:151], 1.0 op_sel_hi:[1,0]
	v_pk_add_f32 v[236:237], v[152:153], 1.0 op_sel_hi:[1,0]
	v_pk_fma_f32 v[18:19], v[18:19], v[234:235], v[166:167]
	v_pk_fma_f32 v[20:21], v[20:21], v[236:237], v[168:169]
	v_cvt_pk_bf16_f32 v18, v18, v19
	v_cvt_pk_bf16_f32 v19, v20, v21
	global_store_dwordx2 v241, v[18:19], s[18:19] offset:2048
	v_mul_f32_e32 v22, v233, v22
	v_mul_f32_e32 v23, v233, v23
	v_mul_f32_e32 v24, v233, v24
	v_mul_f32_e32 v25, v233, v25
	v_pk_mul_f32 v[22:23], v[22:23], v[138:139]
	v_pk_mul_f32 v[24:25], v[24:25], v[140:141]
	v_pk_add_f32 v[234:235], v[154:155], 1.0 op_sel_hi:[1,0]
	v_pk_add_f32 v[236:237], v[156:157], 1.0 op_sel_hi:[1,0]
	v_pk_fma_f32 v[22:23], v[22:23], v[234:235], v[170:171]
	v_pk_fma_f32 v[24:25], v[24:25], v[236:237], v[172:173]
	v_cvt_pk_bf16_f32 v22, v22, v23
	v_cvt_pk_bf16_f32 v23, v24, v25
	global_store_dwordx2 v241, v[22:23], s[18:19] offset:2560
	v_mul_f32_e32 v26, v233, v26
	v_mul_f32_e32 v27, v233, v27
	v_mul_f32_e32 v28, v233, v28
	v_mul_f32_e32 v29, v233, v29
	v_pk_mul_f32 v[26:27], v[26:27], v[142:143]
	v_pk_mul_f32 v[28:29], v[28:29], v[144:145]
	v_pk_add_f32 v[234:235], v[158:159], 1.0 op_sel_hi:[1,0]
	v_pk_add_f32 v[236:237], v[160:161], 1.0 op_sel_hi:[1,0]
	v_pk_fma_f32 v[26:27], v[26:27], v[234:235], v[174:175]
	v_pk_fma_f32 v[28:29], v[28:29], v[236:237], v[176:177]
	v_cvt_pk_bf16_f32 v26, v26, v27
	v_cvt_pk_bf16_f32 v27, v28, v29
	global_store_dwordx2 v241, v[26:27], s[18:19] offset:3072
	v_mul_f32_e32 v30, v233, v30
	v_mul_f32_e32 v31, v233, v31
	v_mul_f32_e32 v32, v233, v32
	v_mul_f32_e32 v33, v233, v33
	v_pk_mul_f32 v[30:31], v[30:31], v[146:147]
	v_pk_mul_f32 v[32:33], v[32:33], v[148:149]
	v_pk_add_f32 v[234:235], v[162:163], 1.0 op_sel_hi:[1,0]
	v_pk_add_f32 v[236:237], v[164:165], 1.0 op_sel_hi:[1,0]
	v_pk_fma_f32 v[30:31], v[30:31], v[234:235], v[178:179]
	v_pk_fma_f32 v[32:33], v[32:33], v[236:237], v[180:181]
	v_cvt_pk_bf16_f32 v30, v30, v31
	v_cvt_pk_bf16_f32 v31, v32, v33
	global_store_dwordx2 v241, v[30:31], s[18:19] offset:3584
	s_cmp_le_u32 s7, 1
	s_cbranch_scc1 .Lnb0_alldone
	s_mul_i32 s6, s42, 1
	s_add_u32 s6, s6, s25
	s_add_u32 s26, s6, s42
	s_min_u32 s26, s26, 2047
	s_load_dwordx2 s[20:21], s[0:1], 0x130
	s_lshr_b32 s27, s26, 9
	s_max_u32 s27, s27, 1
	s_sub_u32 s27, s27, 1
	s_mul_i32 s28, s62, 3
	s_add_u32 s27, s27, s28
	s_mul_i32 s27, s27, 24576
	s_waitcnt lgkmcnt(0)
	s_add_u32 s20, s20, s27
	s_addc_u32 s21, s21, 0
	s_add_u32 s18, s20, 0x1000
	s_addc_u32 s19, s21, 0
	global_load_dwordx4 v[150:153], v195, s[18:19]
	global_load_dwordx4 v[154:157], v195, s[18:19] offset:1024
	global_load_dwordx4 v[158:161], v195, s[18:19] offset:2048
	global_load_dwordx4 v[162:165], v195, s[18:19] offset:3072
	global_load_dwordx4 v[166:169], v195, s[20:21]
	global_load_dwordx4 v[170:173], v195, s[20:21] offset:1024
	global_load_dwordx4 v[174:177], v195, s[20:21] offset:2048
	global_load_dwordx4 v[178:181], v195, s[20:21] offset:3072
	s_waitcnt vmcnt(16)
	v_pk_mul_f32 v[234:235], v[34:35], v[34:35]
	v_pk_mul_f32 v[236:237], v[36:37], v[36:37]
	v_pk_fma_f32 v[234:235], v[38:39], v[38:39], v[234:235]
	v_pk_fma_f32 v[236:237], v[40:41], v[40:41], v[236:237]
	v_pk_fma_f32 v[234:235], v[42:43], v[42:43], v[234:235]
	v_pk_fma_f32 v[236:237], v[44:45], v[44:45], v[236:237]
	v_pk_fma_f32 v[234:235], v[46:47], v[46:47], v[234:235]
	v_pk_fma_f32 v[236:237], v[48:49], v[48:49], v[236:237]
	v_pk_add_f32 v[234:235], v[234:235], v[236:237]
	v_add_f32_e32 v232, v234, v235
	v_pk_mul_f32 v[234:235], v[50:51], v[50:51]
	v_pk_mul_f32 v[236:237], v[52:53], v[52:53]
	v_pk_fma_f32 v[234:235], v[54:55], v[54:55], v[234:235]
	v_pk_fma_f32 v[236:237], v[56:57], v[56:57], v[236:237]
	v_pk_fma_f32 v[234:235], v[58:59], v[58:59], v[234:235]
	v_pk_fma_f32 v[236:237], v[60:61], v[60:61], v[236:237]
	v_pk_fma_f32 v[234:235], v[62:63], v[62:63], v[234:235]
	v_pk_fma_f32 v[236:237], v[64:65], v[64:65], v[236:237]
	v_pk_add_f32 v[234:235], v[234:235], v[236:237]
	v_add_f32_e32 v233, v234, v235
	s_nop 1
	v_add_f32_dpp v232, v232, v232 quad_perm:[1,0,3,2] row_mask:0xf bank_mask:0xf bound_ctrl:1
	s_nop 1
	v_add_f32_dpp v232, v232, v232 quad_perm:[2,3,0,1] row_mask:0xf bank_mask:0xf bound_ctrl:1
	s_nop 1
	v_add_f32_dpp v232, v232, v232 row_half_mirror row_mask:0xf bank_mask:0xf bound_ctrl:1
	s_nop 1
	v_add_f32_dpp v232, v232, v232 row_mirror row_mask:0xf bank_mask:0xf bound_ctrl:1
	s_nop 1
	v_readlane_b32 s18, v232, 0
	v_readlane_b32 s19, v232, 16
	v_readlane_b32 s27, v232, 32
	v_readlane_b32 s28, v232, 48
	s_nop 3
	v_mov_b32_e32 v234, s19
	v_mov_b32_e32 v235, s28
	v_add_f32_e32 v234, s18, v234
	v_add_f32_e32 v235, s27, v235
	v_add_f32_e32 v234, v234, v235
	v_mov_b32_e32 v235, 0x3a800000
	v_fma_f32 v234, v234, v235, v132
	v_rsq_f32_e32 v232, v234
	s_nop 1
	v_add_f32_dpp v233, v233, v233 quad_perm:[1,0,3,2] row_mask:0xf bank_mask:0xf bound_ctrl:1
	s_nop 1
	v_add_f32_dpp v233, v233, v233 quad_perm:[2,3,0,1] row_mask:0xf bank_mask:0xf bound_ctrl:1
	s_nop 1
	v_add_f32_dpp v233, v233, v233 row_half_mirror row_mask:0xf bank_mask:0xf bound_ctrl:1
	s_nop 1
	v_add_f32_dpp v233, v233, v233 row_mirror row_mask:0xf bank_mask:0xf bound_ctrl:1
	s_nop 1
	v_readlane_b32 s18, v233, 0
	v_readlane_b32 s19, v233, 16
	v_readlane_b32 s27, v233, 32
	v_readlane_b32 s28, v233, 48
	s_nop 3
	v_mov_b32_e32 v234, s19
	v_mov_b32_e32 v235, s28
	v_add_f32_e32 v234, s18, v234
	v_add_f32_e32 v235, s27, v235
	v_add_f32_e32 v234, v234, v235
	v_mov_b32_e32 v235, 0x3a800000
	v_fma_f32 v234, v234, v235, v132
	v_rsq_f32_e32 v233, v234
	s_load_dwordx2 s[18:19], s[0:1], 0x130
	s_lshl_b32 s27, s6, 3
	s_add_u32 s27, s27, s29
	s_lshl_b32 s27, s27, 11
	s_add_u32 s27, s27, 0x2b27800
	s_waitcnt lgkmcnt(0)
	s_add_u32 s18, s18, s27
	s_addc_u32 s19, s19, 0
	v_mul_f32_e32 v34, v232, v34
	v_mul_f32_e32 v35, v232, v35
	v_mul_f32_e32 v36, v232, v36
	v_mul_f32_e32 v37, v232, v37
	v_pk_mul_f32 v[34:35], v[34:35], v[134:135]
	v_pk_mul_f32 v[36:37], v[36:37], v[136:137]
	v_pk_add_f32 v[234:235], v[196:197], 1.0 op_sel_hi:[1,0]
	v_pk_add_f32 v[236:237], v[198:199], 1.0 op_sel_hi:[1,0]
	v_pk_fma_f32 v[34:35], v[34:35], v[234:235], v[216:217]
	v_pk_fma_f32 v[36:37], v[36:37], v[236:237], v[218:219]
	v_cvt_pk_bf16_f32 v34, v34, v35
	v_cvt_pk_bf16_f32 v35, v36, v37
	global_store_dwordx2 v241, v[34:35], s[18:19] offset:0
	v_mul_f32_e32 v38, v232, v38
	v_mul_f32_e32 v39, v232, v39
	v_mul_f32_e32 v40, v232, v40
	v_mul_f32_e32 v41, v232, v41
	v_pk_mul_f32 v[38:39], v[38:39], v[138:139]
	v_pk_mul_f32 v[40:41], v[40:41], v[140:141]
	v_pk_add_f32 v[234:235], v[200:201], 1.0 op_sel_hi:[1,0]
	v_pk_add_f32 v[236:237], v[202:203], 1.0 op_sel_hi:[1,0]
	v_pk_fma_f32 v[38:39], v[38:39], v[234:235], v[220:221]
	v_pk_fma_f32 v[40:41], v[40:41], v[236:237], v[222:223]
	v_cvt_pk_bf16_f32 v38, v38, v39
	v_cvt_pk_bf16_f32 v39, v40, v41
	global_store_dwordx2 v241, v[38:39], s[18:19] offset:512
	v_mul_f32_e32 v42, v232, v42
	v_mul_f32_e32 v43, v232, v43
	v_mul_f32_e32 v44, v232, v44
	v_mul_f32_e32 v45, v232, v45
	v_pk_mul_f32 v[42:43], v[42:43], v[142:143]
	v_pk_mul_f32 v[44:45], v[44:45], v[144:145]
	v_pk_add_f32 v[234:235], v[204:205], 1.0 op_sel_hi:[1,0]
	v_pk_add_f32 v[236:237], v[206:207], 1.0 op_sel_hi:[1,0]
	v_pk_fma_f32 v[42:43], v[42:43], v[234:235], v[224:225]
	v_pk_fma_f32 v[44:45], v[44:45], v[236:237], v[226:227]
	v_cvt_pk_bf16_f32 v42, v42, v43
	v_cvt_pk_bf16_f32 v43, v44, v45
	global_store_dwordx2 v241, v[42:43], s[18:19] offset:1024
	v_mul_f32_e32 v46, v232, v46
	v_mul_f32_e32 v47, v232, v47
	v_mul_f32_e32 v48, v232, v48
	v_mul_f32_e32 v49, v232, v49
	v_pk_mul_f32 v[46:47], v[46:47], v[146:147]
	v_pk_mul_f32 v[48:49], v[48:49], v[148:149]
	v_pk_add_f32 v[234:235], v[212:213], 1.0 op_sel_hi:[1,0]
	v_pk_add_f32 v[236:237], v[214:215], 1.0 op_sel_hi:[1,0]
	v_pk_fma_f32 v[46:47], v[46:47], v[234:235], v[228:229]
	v_pk_fma_f32 v[48:49], v[48:49], v[236:237], v[230:231]
	v_cvt_pk_bf16_f32 v46, v46, v47
	v_cvt_pk_bf16_f32 v47, v48, v49
	global_store_dwordx2 v241, v[46:47], s[18:19] offset:1536
	v_mul_f32_e32 v50, v233, v50
	v_mul_f32_e32 v51, v233, v51
	v_mul_f32_e32 v52, v233, v52
	v_mul_f32_e32 v53, v233, v53
	v_pk_mul_f32 v[50:51], v[50:51], v[134:135]
	v_pk_mul_f32 v[52:53], v[52:53], v[136:137]
	v_pk_add_f32 v[234:235], v[196:197], 1.0 op_sel_hi:[1,0]
	v_pk_add_f32 v[236:237], v[198:199], 1.0 op_sel_hi:[1,0]
	v_pk_fma_f32 v[50:51], v[50:51], v[234:235], v[216:217]
	v_pk_fma_f32 v[52:53], v[52:53], v[236:237], v[218:219]
	v_cvt_pk_bf16_f32 v50, v50, v51
	v_cvt_pk_bf16_f32 v51, v52, v53
	global_store_dwordx2 v241, v[50:51], s[18:19] offset:2048
	v_mul_f32_e32 v54, v233, v54
	v_mul_f32_e32 v55, v233, v55
	v_mul_f32_e32 v56, v233, v56
	v_mul_f32_e32 v57, v233, v57
	v_pk_mul_f32 v[54:55], v[54:55], v[138:139]
	v_pk_mul_f32 v[56:57], v[56:57], v[140:141]
	v_pk_add_f32 v[234:235], v[200:201], 1.0 op_sel_hi:[1,0]
	v_pk_add_f32 v[236:237], v[202:203], 1.0 op_sel_hi:[1,0]
	v_pk_fma_f32 v[54:55], v[54:55], v[234:235], v[220:221]
	v_pk_fma_f32 v[56:57], v[56:57], v[236:237], v[222:223]
	v_cvt_pk_bf16_f32 v54, v54, v55
	v_cvt_pk_bf16_f32 v55, v56, v57
	global_store_dwordx2 v241, v[54:55], s[18:19] offset:2560
	v_mul_f32_e32 v58, v233, v58
	v_mul_f32_e32 v59, v233, v59
	v_mul_f32_e32 v60, v233, v60
	v_mul_f32_e32 v61, v233, v61
	v_pk_mul_f32 v[58:59], v[58:59], v[142:143]
	v_pk_mul_f32 v[60:61], v[60:61], v[144:145]
	v_pk_add_f32 v[234:235], v[204:205], 1.0 op_sel_hi:[1,0]
	v_pk_add_f32 v[236:237], v[206:207], 1.0 op_sel_hi:[1,0]
	v_pk_fma_f32 v[58:59], v[58:59], v[234:235], v[224:225]
	v_pk_fma_f32 v[60:61], v[60:61], v[236:237], v[226:227]
	v_cvt_pk_bf16_f32 v58, v58, v59
	v_cvt_pk_bf16_f32 v59, v60, v61
	global_store_dwordx2 v241, v[58:59], s[18:19] offset:3072
	v_mul_f32_e32 v62, v233, v62
	v_mul_f32_e32 v63, v233, v63
	v_mul_f32_e32 v64, v233, v64
	v_mul_f32_e32 v65, v233, v65
	v_pk_mul_f32 v[62:63], v[62:63], v[146:147]
	v_pk_mul_f32 v[64:65], v[64:65], v[148:149]
	v_pk_add_f32 v[234:235], v[212:213], 1.0 op_sel_hi:[1,0]
	v_pk_add_f32 v[236:237], v[214:215], 1.0 op_sel_hi:[1,0]
	v_pk_fma_f32 v[62:63], v[62:63], v[234:235], v[228:229]
	v_pk_fma_f32 v[64:65], v[64:65], v[236:237], v[230:231]
	v_cvt_pk_bf16_f32 v62, v62, v63
	v_cvt_pk_bf16_f32 v63, v64, v65
	global_store_dwordx2 v241, v[62:63], s[18:19] offset:3584
	s_cmp_le_u32 s7, 2
	s_cbranch_scc1 .Lnb0_alldone
	s_mul_i32 s6, s42, 2
	s_add_u32 s6, s6, s25
	s_add_u32 s26, s6, s42
	s_min_u32 s26, s26, 2047
	s_load_dwordx2 s[20:21], s[0:1], 0x130
	s_lshr_b32 s27, s26, 9
	s_max_u32 s27, s27, 1
	s_sub_u32 s27, s27, 1
	s_mul_i32 s28, s62, 3
	s_add_u32 s27, s27, s28
	s_mul_i32 s27, s27, 24576
	s_waitcnt lgkmcnt(0)
	s_add_u32 s20, s20, s27
	s_addc_u32 s21, s21, 0
	s_add_u32 s18, s20, 0x1000
	s_addc_u32 s19, s21, 0
	global_load_dwordx4 v[196:199], v195, s[18:19]
	global_load_dwordx4 v[200:203], v195, s[18:19] offset:1024
	global_load_dwordx4 v[204:207], v195, s[18:19] offset:2048
	global_load_dwordx4 v[212:215], v195, s[18:19] offset:3072
	global_load_dwordx4 v[216:219], v195, s[20:21]
	global_load_dwordx4 v[220:223], v195, s[20:21] offset:1024
	global_load_dwordx4 v[224:227], v195, s[20:21] offset:2048
	global_load_dwordx4 v[228:231], v195, s[20:21] offset:3072
	s_waitcnt vmcnt(16)
	v_pk_mul_f32 v[234:235], v[66:67], v[66:67]
	v_pk_mul_f32 v[236:237], v[68:69], v[68:69]
	v_pk_fma_f32 v[234:235], v[70:71], v[70:71], v[234:235]
	v_pk_fma_f32 v[236:237], v[72:73], v[72:73], v[236:237]
	v_pk_fma_f32 v[234:235], v[74:75], v[74:75], v[234:235]
	v_pk_fma_f32 v[236:237], v[76:77], v[76:77], v[236:237]
	v_pk_fma_f32 v[234:235], v[78:79], v[78:79], v[234:235]
	v_pk_fma_f32 v[236:237], v[80:81], v[80:81], v[236:237]
	v_pk_add_f32 v[234:235], v[234:235], v[236:237]
	v_add_f32_e32 v232, v234, v235
	v_pk_mul_f32 v[234:235], v[82:83], v[82:83]
	v_pk_mul_f32 v[236:237], v[84:85], v[84:85]
	v_pk_fma_f32 v[234:235], v[86:87], v[86:87], v[234:235]
	v_pk_fma_f32 v[236:237], v[88:89], v[88:89], v[236:237]
	v_pk_fma_f32 v[234:235], v[90:91], v[90:91], v[234:235]
	v_pk_fma_f32 v[236:237], v[92:93], v[92:93], v[236:237]
	v_pk_fma_f32 v[234:235], v[94:95], v[94:95], v[234:235]
	v_pk_fma_f32 v[236:237], v[96:97], v[96:97], v[236:237]
	v_pk_add_f32 v[234:235], v[234:235], v[236:237]
	v_add_f32_e32 v233, v234, v235
	s_nop 1
	v_add_f32_dpp v232, v232, v232 quad_perm:[1,0,3,2] row_mask:0xf bank_mask:0xf bound_ctrl:1
	s_nop 1
	v_add_f32_dpp v232, v232, v232 quad_perm:[2,3,0,1] row_mask:0xf bank_mask:0xf bound_ctrl:1
	s_nop 1
	v_add_f32_dpp v232, v232, v232 row_half_mirror row_mask:0xf bank_mask:0xf bound_ctrl:1
	s_nop 1
	v_add_f32_dpp v232, v232, v232 row_mirror row_mask:0xf bank_mask:0xf bound_ctrl:1
	s_nop 1
	v_readlane_b32 s18, v232, 0
	v_readlane_b32 s19, v232, 16
	v_readlane_b32 s27, v232, 32
	v_readlane_b32 s28, v232, 48
	s_nop 3
	v_mov_b32_e32 v234, s19
	v_mov_b32_e32 v235, s28
	v_add_f32_e32 v234, s18, v234
	v_add_f32_e32 v235, s27, v235
	v_add_f32_e32 v234, v234, v235
	v_mov_b32_e32 v235, 0x3a800000
	v_fma_f32 v234, v234, v235, v132
	v_rsq_f32_e32 v232, v234
	s_nop 1
	v_add_f32_dpp v233, v233, v233 quad_perm:[1,0,3,2] row_mask:0xf bank_mask:0xf bound_ctrl:1
	s_nop 1
	v_add_f32_dpp v233, v233, v233 quad_perm:[2,3,0,1] row_mask:0xf bank_mask:0xf bound_ctrl:1
	s_nop 1
	v_add_f32_dpp v233, v233, v233 row_half_mirror row_mask:0xf bank_mask:0xf bound_ctrl:1
	s_nop 1
	v_add_f32_dpp v233, v233, v233 row_mirror row_mask:0xf bank_mask:0xf bound_ctrl:1
	s_nop 1
	v_readlane_b32 s18, v233, 0
	v_readlane_b32 s19, v233, 16
	v_readlane_b32 s27, v233, 32
	v_readlane_b32 s28, v233, 48
	s_nop 3
	v_mov_b32_e32 v234, s19
	v_mov_b32_e32 v235, s28
	v_add_f32_e32 v234, s18, v234
	v_add_f32_e32 v235, s27, v235
	v_add_f32_e32 v234, v234, v235
	v_mov_b32_e32 v235, 0x3a800000
	v_fma_f32 v234, v234, v235, v132
	v_rsq_f32_e32 v233, v234
	s_load_dwordx2 s[18:19], s[0:1], 0x130
	s_lshl_b32 s27, s6, 3
	s_add_u32 s27, s27, s29
	s_lshl_b32 s27, s27, 11
	s_add_u32 s27, s27, 0x2b27800
	s_waitcnt lgkmcnt(0)
	s_add_u32 s18, s18, s27
	s_addc_u32 s19, s19, 0
	v_mul_f32_e32 v66, v232, v66
	v_mul_f32_e32 v67, v232, v67
	v_mul_f32_e32 v68, v232, v68
	v_mul_f32_e32 v69, v232, v69
	v_pk_mul_f32 v[66:67], v[66:67], v[134:135]
	v_pk_mul_f32 v[68:69], v[68:69], v[136:137]
	v_pk_add_f32 v[234:235], v[150:151], 1.0 op_sel_hi:[1,0]
	v_pk_add_f32 v[236:237], v[152:153], 1.0 op_sel_hi:[1,0]
	v_pk_fma_f32 v[66:67], v[66:67], v[234:235], v[166:167]
	v_pk_fma_f32 v[68:69], v[68:69], v[236:237], v[168:169]
	v_cvt_pk_bf16_f32 v66, v66, v67
	v_cvt_pk_bf16_f32 v67, v68, v69
	global_store_dwordx2 v241, v[66:67], s[18:19] offset:0
	v_mul_f32_e32 v70, v232, v70
	v_mul_f32_e32 v71, v232, v71
	v_mul_f32_e32 v72, v232, v72
	v_mul_f32_e32 v73, v232, v73
	v_pk_mul_f32 v[70:71], v[70:71], v[138:139]
	v_pk_mul_f32 v[72:73], v[72:73], v[140:141]
	v_pk_add_f32 v[234:235], v[154:155], 1.0 op_sel_hi:[1,0]
	v_pk_add_f32 v[236:237], v[156:157], 1.0 op_sel_hi:[1,0]
	v_pk_fma_f32 v[70:71], v[70:71], v[234:235], v[170:171]
	v_pk_fma_f32 v[72:73], v[72:73], v[236:237], v[172:173]
	v_cvt_pk_bf16_f32 v70, v70, v71
	v_cvt_pk_bf16_f32 v71, v72, v73
	global_store_dwordx2 v241, v[70:71], s[18:19] offset:512
	v_mul_f32_e32 v74, v232, v74
	v_mul_f32_e32 v75, v232, v75
	v_mul_f32_e32 v76, v232, v76
	v_mul_f32_e32 v77, v232, v77
	v_pk_mul_f32 v[74:75], v[74:75], v[142:143]
	v_pk_mul_f32 v[76:77], v[76:77], v[144:145]
	v_pk_add_f32 v[234:235], v[158:159], 1.0 op_sel_hi:[1,0]
	v_pk_add_f32 v[236:237], v[160:161], 1.0 op_sel_hi:[1,0]
	v_pk_fma_f32 v[74:75], v[74:75], v[234:235], v[174:175]
	v_pk_fma_f32 v[76:77], v[76:77], v[236:237], v[176:177]
	v_cvt_pk_bf16_f32 v74, v74, v75
	v_cvt_pk_bf16_f32 v75, v76, v77
	global_store_dwordx2 v241, v[74:75], s[18:19] offset:1024
	v_mul_f32_e32 v78, v232, v78
	v_mul_f32_e32 v79, v232, v79
	v_mul_f32_e32 v80, v232, v80
	v_mul_f32_e32 v81, v232, v81
	v_pk_mul_f32 v[78:79], v[78:79], v[146:147]
	v_pk_mul_f32 v[80:81], v[80:81], v[148:149]
	v_pk_add_f32 v[234:235], v[162:163], 1.0 op_sel_hi:[1,0]
	v_pk_add_f32 v[236:237], v[164:165], 1.0 op_sel_hi:[1,0]
	v_pk_fma_f32 v[78:79], v[78:79], v[234:235], v[178:179]
	v_pk_fma_f32 v[80:81], v[80:81], v[236:237], v[180:181]
	v_cvt_pk_bf16_f32 v78, v78, v79
	v_cvt_pk_bf16_f32 v79, v80, v81
	global_store_dwordx2 v241, v[78:79], s[18:19] offset:1536
	v_mul_f32_e32 v82, v233, v82
	v_mul_f32_e32 v83, v233, v83
	v_mul_f32_e32 v84, v233, v84
	v_mul_f32_e32 v85, v233, v85
	v_pk_mul_f32 v[82:83], v[82:83], v[134:135]
	v_pk_mul_f32 v[84:85], v[84:85], v[136:137]
	v_pk_add_f32 v[234:235], v[150:151], 1.0 op_sel_hi:[1,0]
	v_pk_add_f32 v[236:237], v[152:153], 1.0 op_sel_hi:[1,0]
	v_pk_fma_f32 v[82:83], v[82:83], v[234:235], v[166:167]
	v_pk_fma_f32 v[84:85], v[84:85], v[236:237], v[168:169]
	v_cvt_pk_bf16_f32 v82, v82, v83
	v_cvt_pk_bf16_f32 v83, v84, v85
	global_store_dwordx2 v241, v[82:83], s[18:19] offset:2048
	v_mul_f32_e32 v86, v233, v86
	v_mul_f32_e32 v87, v233, v87
	v_mul_f32_e32 v88, v233, v88
	v_mul_f32_e32 v89, v233, v89
	v_pk_mul_f32 v[86:87], v[86:87], v[138:139]
	v_pk_mul_f32 v[88:89], v[88:89], v[140:141]
	v_pk_add_f32 v[234:235], v[154:155], 1.0 op_sel_hi:[1,0]
	v_pk_add_f32 v[236:237], v[156:157], 1.0 op_sel_hi:[1,0]
	v_pk_fma_f32 v[86:87], v[86:87], v[234:235], v[170:171]
	v_pk_fma_f32 v[88:89], v[88:89], v[236:237], v[172:173]
	v_cvt_pk_bf16_f32 v86, v86, v87
	v_cvt_pk_bf16_f32 v87, v88, v89
	global_store_dwordx2 v241, v[86:87], s[18:19] offset:2560
	v_mul_f32_e32 v90, v233, v90
	v_mul_f32_e32 v91, v233, v91
	v_mul_f32_e32 v92, v233, v92
	v_mul_f32_e32 v93, v233, v93
	v_pk_mul_f32 v[90:91], v[90:91], v[142:143]
	v_pk_mul_f32 v[92:93], v[92:93], v[144:145]
	v_pk_add_f32 v[234:235], v[158:159], 1.0 op_sel_hi:[1,0]
	v_pk_add_f32 v[236:237], v[160:161], 1.0 op_sel_hi:[1,0]
	v_pk_fma_f32 v[90:91], v[90:91], v[234:235], v[174:175]
	v_pk_fma_f32 v[92:93], v[92:93], v[236:237], v[176:177]
	v_cvt_pk_bf16_f32 v90, v90, v91
	v_cvt_pk_bf16_f32 v91, v92, v93
	global_store_dwordx2 v241, v[90:91], s[18:19] offset:3072
	v_mul_f32_e32 v94, v233, v94
	v_mul_f32_e32 v95, v233, v95
	v_mul_f32_e32 v96, v233, v96
	v_mul_f32_e32 v97, v233, v97
	v_pk_mul_f32 v[94:95], v[94:95], v[146:147]
	v_pk_mul_f32 v[96:97], v[96:97], v[148:149]
	v_pk_add_f32 v[234:235], v[162:163], 1.0 op_sel_hi:[1,0]
	v_pk_add_f32 v[236:237], v[164:165], 1.0 op_sel_hi:[1,0]
	v_pk_fma_f32 v[94:95], v[94:95], v[234:235], v[178:179]
	v_pk_fma_f32 v[96:97], v[96:97], v[236:237], v[180:181]
	v_cvt_pk_bf16_f32 v94, v94, v95
	v_cvt_pk_bf16_f32 v95, v96, v97
	global_store_dwordx2 v241, v[94:95], s[18:19] offset:3584
	s_cmp_le_u32 s7, 3
	s_cbranch_scc1 .Lnb0_alldone
	s_mul_i32 s6, s42, 3
	s_add_u32 s6, s6, s25
	s_waitcnt vmcnt(8)
	v_pk_mul_f32 v[234:235], v[98:99], v[98:99]
	v_pk_mul_f32 v[236:237], v[100:101], v[100:101]
	v_pk_fma_f32 v[234:235], v[102:103], v[102:103], v[234:235]
	v_pk_fma_f32 v[236:237], v[104:105], v[104:105], v[236:237]
	v_pk_fma_f32 v[234:235], v[106:107], v[106:107], v[234:235]
	v_pk_fma_f32 v[236:237], v[108:109], v[108:109], v[236:237]
	v_pk_fma_f32 v[234:235], v[110:111], v[110:111], v[234:235]
	v_pk_fma_f32 v[236:237], v[112:113], v[112:113], v[236:237]
	v_pk_add_f32 v[234:235], v[234:235], v[236:237]
	v_add_f32_e32 v232, v234, v235
	v_pk_mul_f32 v[234:235], v[114:115], v[114:115]
	v_pk_mul_f32 v[236:237], v[116:117], v[116:117]
	v_pk_fma_f32 v[234:235], v[118:119], v[118:119], v[234:235]
	v_pk_fma_f32 v[236:237], v[120:121], v[120:121], v[236:237]
	v_pk_fma_f32 v[234:235], v[122:123], v[122:123], v[234:235]
	v_pk_fma_f32 v[236:237], v[124:125], v[124:125], v[236:237]
	v_pk_fma_f32 v[234:235], v[126:127], v[126:127], v[234:235]
	v_pk_fma_f32 v[236:237], v[128:129], v[128:129], v[236:237]
	v_pk_add_f32 v[234:235], v[234:235], v[236:237]
	v_add_f32_e32 v233, v234, v235
	s_nop 1
	v_add_f32_dpp v232, v232, v232 quad_perm:[1,0,3,2] row_mask:0xf bank_mask:0xf bound_ctrl:1
	s_nop 1
	v_add_f32_dpp v232, v232, v232 quad_perm:[2,3,0,1] row_mask:0xf bank_mask:0xf bound_ctrl:1
	s_nop 1
	v_add_f32_dpp v232, v232, v232 row_half_mirror row_mask:0xf bank_mask:0xf bound_ctrl:1
	s_nop 1
	v_add_f32_dpp v232, v232, v232 row_mirror row_mask:0xf bank_mask:0xf bound_ctrl:1
	s_nop 1
	v_readlane_b32 s18, v232, 0
	v_readlane_b32 s19, v232, 16
	v_readlane_b32 s27, v232, 32
	v_readlane_b32 s28, v232, 48
	s_nop 3
	v_mov_b32_e32 v234, s19
	v_mov_b32_e32 v235, s28
	v_add_f32_e32 v234, s18, v234
	v_add_f32_e32 v235, s27, v235
	v_add_f32_e32 v234, v234, v235
	v_mov_b32_e32 v235, 0x3a800000
	v_fma_f32 v234, v234, v235, v132
	v_rsq_f32_e32 v232, v234
	s_nop 1
	v_add_f32_dpp v233, v233, v233 quad_perm:[1,0,3,2] row_mask:0xf bank_mask:0xf bound_ctrl:1
	s_nop 1
	v_add_f32_dpp v233, v233, v233 quad_perm:[2,3,0,1] row_mask:0xf bank_mask:0xf bound_ctrl:1
	s_nop 1
	v_add_f32_dpp v233, v233, v233 row_half_mirror row_mask:0xf bank_mask:0xf bound_ctrl:1
	s_nop 1
	v_add_f32_dpp v233, v233, v233 row_mirror row_mask:0xf bank_mask:0xf bound_ctrl:1
	s_nop 1
	v_readlane_b32 s18, v233, 0
	v_readlane_b32 s19, v233, 16
	v_readlane_b32 s27, v233, 32
	v_readlane_b32 s28, v233, 48
	s_nop 3
	v_mov_b32_e32 v234, s19
	v_mov_b32_e32 v235, s28
	v_add_f32_e32 v234, s18, v234
	v_add_f32_e32 v235, s27, v235
	v_add_f32_e32 v234, v234, v235
	v_mov_b32_e32 v235, 0x3a800000
	v_fma_f32 v234, v234, v235, v132
	v_rsq_f32_e32 v233, v234
	s_load_dwordx2 s[18:19], s[0:1], 0x130
	s_lshl_b32 s27, s6, 3
	s_add_u32 s27, s27, s29
	s_lshl_b32 s27, s27, 11
	s_add_u32 s27, s27, 0x2b27800
	s_waitcnt lgkmcnt(0)
	s_add_u32 s18, s18, s27
	s_addc_u32 s19, s19, 0
	v_mul_f32_e32 v98, v232, v98
	v_mul_f32_e32 v99, v232, v99
	v_mul_f32_e32 v100, v232, v100
	v_mul_f32_e32 v101, v232, v101
	v_pk_mul_f32 v[98:99], v[98:99], v[134:135]
	v_pk_mul_f32 v[100:101], v[100:101], v[136:137]
	v_pk_add_f32 v[234:235], v[196:197], 1.0 op_sel_hi:[1,0]
	v_pk_add_f32 v[236:237], v[198:199], 1.0 op_sel_hi:[1,0]
	v_pk_fma_f32 v[98:99], v[98:99], v[234:235], v[216:217]
	v_pk_fma_f32 v[100:101], v[100:101], v[236:237], v[218:219]
	v_cvt_pk_bf16_f32 v98, v98, v99
	v_cvt_pk_bf16_f32 v99, v100, v101
	global_store_dwordx2 v241, v[98:99], s[18:19] offset:0
	v_mul_f32_e32 v102, v232, v102
	v_mul_f32_e32 v103, v232, v103
	v_mul_f32_e32 v104, v232, v104
	v_mul_f32_e32 v105, v232, v105
	v_pk_mul_f32 v[102:103], v[102:103], v[138:139]
	v_pk_mul_f32 v[104:105], v[104:105], v[140:141]
	v_pk_add_f32 v[234:235], v[200:201], 1.0 op_sel_hi:[1,0]
	v_pk_add_f32 v[236:237], v[202:203], 1.0 op_sel_hi:[1,0]
	v_pk_fma_f32 v[102:103], v[102:103], v[234:235], v[220:221]
	v_pk_fma_f32 v[104:105], v[104:105], v[236:237], v[222:223]
	v_cvt_pk_bf16_f32 v102, v102, v103
	v_cvt_pk_bf16_f32 v103, v104, v105
	global_store_dwordx2 v241, v[102:103], s[18:19] offset:512
	v_mul_f32_e32 v106, v232, v106
	v_mul_f32_e32 v107, v232, v107
	v_mul_f32_e32 v108, v232, v108
	v_mul_f32_e32 v109, v232, v109
	v_pk_mul_f32 v[106:107], v[106:107], v[142:143]
	v_pk_mul_f32 v[108:109], v[108:109], v[144:145]
	v_pk_add_f32 v[234:235], v[204:205], 1.0 op_sel_hi:[1,0]
	v_pk_add_f32 v[236:237], v[206:207], 1.0 op_sel_hi:[1,0]
	v_pk_fma_f32 v[106:107], v[106:107], v[234:235], v[224:225]
	v_pk_fma_f32 v[108:109], v[108:109], v[236:237], v[226:227]
	v_cvt_pk_bf16_f32 v106, v106, v107
	v_cvt_pk_bf16_f32 v107, v108, v109
	global_store_dwordx2 v241, v[106:107], s[18:19] offset:1024
	v_mul_f32_e32 v110, v232, v110
	v_mul_f32_e32 v111, v232, v111
	v_mul_f32_e32 v112, v232, v112
	v_mul_f32_e32 v113, v232, v113
	v_pk_mul_f32 v[110:111], v[110:111], v[146:147]
	v_pk_mul_f32 v[112:113], v[112:113], v[148:149]
	v_pk_add_f32 v[234:235], v[212:213], 1.0 op_sel_hi:[1,0]
	v_pk_add_f32 v[236:237], v[214:215], 1.0 op_sel_hi:[1,0]
	v_pk_fma_f32 v[110:111], v[110:111], v[234:235], v[228:229]
	v_pk_fma_f32 v[112:113], v[112:113], v[236:237], v[230:231]
	v_cvt_pk_bf16_f32 v110, v110, v111
	v_cvt_pk_bf16_f32 v111, v112, v113
	global_store_dwordx2 v241, v[110:111], s[18:19] offset:1536
	v_mul_f32_e32 v114, v233, v114
	v_mul_f32_e32 v115, v233, v115
	v_mul_f32_e32 v116, v233, v116
	v_mul_f32_e32 v117, v233, v117
	v_pk_mul_f32 v[114:115], v[114:115], v[134:135]
	v_pk_mul_f32 v[116:117], v[116:117], v[136:137]
	v_pk_add_f32 v[234:235], v[196:197], 1.0 op_sel_hi:[1,0]
	v_pk_add_f32 v[236:237], v[198:199], 1.0 op_sel_hi:[1,0]
	v_pk_fma_f32 v[114:115], v[114:115], v[234:235], v[216:217]
	v_pk_fma_f32 v[116:117], v[116:117], v[236:237], v[218:219]
	v_cvt_pk_bf16_f32 v114, v114, v115
	v_cvt_pk_bf16_f32 v115, v116, v117
	global_store_dwordx2 v241, v[114:115], s[18:19] offset:2048
	v_mul_f32_e32 v118, v233, v118
	v_mul_f32_e32 v119, v233, v119
	v_mul_f32_e32 v120, v233, v120
	v_mul_f32_e32 v121, v233, v121
	v_pk_mul_f32 v[118:119], v[118:119], v[138:139]
	v_pk_mul_f32 v[120:121], v[120:121], v[140:141]
	v_pk_add_f32 v[234:235], v[200:201], 1.0 op_sel_hi:[1,0]
	v_pk_add_f32 v[236:237], v[202:203], 1.0 op_sel_hi:[1,0]
	v_pk_fma_f32 v[118:119], v[118:119], v[234:235], v[220:221]
	v_pk_fma_f32 v[120:121], v[120:121], v[236:237], v[222:223]
	v_cvt_pk_bf16_f32 v118, v118, v119
	v_cvt_pk_bf16_f32 v119, v120, v121
	global_store_dwordx2 v241, v[118:119], s[18:19] offset:2560
	v_mul_f32_e32 v122, v233, v122
	v_mul_f32_e32 v123, v233, v123
	v_mul_f32_e32 v124, v233, v124
	v_mul_f32_e32 v125, v233, v125
	v_pk_mul_f32 v[122:123], v[122:123], v[142:143]
	v_pk_mul_f32 v[124:125], v[124:125], v[144:145]
	v_pk_add_f32 v[234:235], v[204:205], 1.0 op_sel_hi:[1,0]
	v_pk_add_f32 v[236:237], v[206:207], 1.0 op_sel_hi:[1,0]
	v_pk_fma_f32 v[122:123], v[122:123], v[234:235], v[224:225]
	v_pk_fma_f32 v[124:125], v[124:125], v[236:237], v[226:227]
	v_cvt_pk_bf16_f32 v122, v122, v123
	v_cvt_pk_bf16_f32 v123, v124, v125
	global_store_dwordx2 v241, v[122:123], s[18:19] offset:3072
	v_mul_f32_e32 v126, v233, v126
	v_mul_f32_e32 v127, v233, v127
	v_mul_f32_e32 v128, v233, v128
	v_mul_f32_e32 v129, v233, v129
	v_pk_mul_f32 v[126:127], v[126:127], v[146:147]
	v_pk_mul_f32 v[128:129], v[128:129], v[148:149]
	v_pk_add_f32 v[234:235], v[212:213], 1.0 op_sel_hi:[1,0]
	v_pk_add_f32 v[236:237], v[214:215], 1.0 op_sel_hi:[1,0]
	v_pk_fma_f32 v[126:127], v[126:127], v[234:235], v[228:229]
	v_pk_fma_f32 v[128:129], v[128:129], v[236:237], v[230:231]
	v_cvt_pk_bf16_f32 v126, v126, v127
	v_cvt_pk_bf16_f32 v127, v128, v129
	global_store_dwordx2 v241, v[126:127], s[18:19] offset:3584

.Lnb0_exit:
	s_mov_b32 s24, s25
	s_branch .LBB0_850
	v_mov_b32_e32 v6, v133
	s_mov_b64 s[6:7], -1
	v_ashrrev_i32_e32 v0, 5, v6
	v_and_b32_e32 v0, -2, v0
	s_waitcnt vmcnt(0)
	v_lshl_add_u32 v36, s24, 3, v0
	s_and_b64 vcc, exec, s[10:11]
	v_ashrrev_i32_e32 v37, 31, v36
	s_cbranch_vccz .LBB0_929
	s_mov_b64 s[6:7], 0
	v_mov_b64_e32 v[2:3], v[36:37]
